# classify prefix by DPP + paired lane-0 atomics; refinement specialised per candidate register count (1..8)
# speedup vs baseline: 1.0599x; 1.0047x over previous
.LBB0_733:
	s_or_b64 exec, exec, s[6:7]
	v_and_b32_e32 v1, 64, v147
	v_cmp_eq_u32_e64 s[6:7], 0, v145
	v_cmp_gt_u32_e64 s[10:11], 32, v145
	v_lshlrev_b32_e32 v10, 2, v147
	v_mov_b32_e32 v5, v4
	s_nop 1
	v_add_u32_dpp v5, v5, v5 row_shr:1 row_mask:0xf bank_mask:0xf
	s_nop 1
	v_add_u32_dpp v5, v5, v5 row_shr:2 row_mask:0xf bank_mask:0xf
	s_nop 1
	v_add_u32_dpp v5, v5, v5 row_shr:4 row_mask:0xf bank_mask:0xf
	s_nop 1
	v_add_u32_dpp v5, v5, v5 row_shr:8 row_mask:0xf bank_mask:0xf
	s_nop 1
	v_add_u32_dpp v5, v5, v5 row_bcast:15 row_mask:0xa bank_mask:0xf
	s_nop 1
	v_add_u32_dpp v5, v5, v5 row_bcast:31 row_mask:0xc bank_mask:0xf
	s_nop 1
	v_readlane_b32 s18, v5, 63
	s_add_i32 s23, s61, 0x25808
	v_mov_b32_e32 v184, s23
	s_and_b32 s19, s18, 0xffff
	s_lshr_b32 s22, s18, 16
	v_mov_b32_e32 v6, s19
	v_mov_b32_e32 v7, s22
	s_mov_b64 exec, 1
	ds_add_rtn_u32 v185, v184, v6
	ds_add_rtn_u32 v186, v184, v7 offset:12
	s_mov_b64 exec, -1
	v_sub_u32_e32 v4, v5, v4
	s_lshl_b32 s92, s90, 9
	s_add_i32 s93, s92, 0x24000
	s_waitcnt lgkmcnt(0)
	v_readfirstlane_b32 s19, v185
	v_readfirstlane_b32 s22, v186
	v_lshrrev_b32_e32 v9, 16, v4
	v_add_u32_e32 v11, s19, v4
	v_add_u32_e32 v9, s22, v9
	s_and_saveexec_b64 s[16:17], s[12:13]
	s_cbranch_execz .LBB0_778
	v_mov_b32_e32 v199, 0x1000
	v_lshlrev_b32_e32 v190, 2, v3
	v_xor_b32_e32 v178, v178, v180
	v_xor_b32_e32 v179, v179, v181

.LBB0_875:
	v_cndmask_b32_e64 v3, 0, 1, s[14:15]
	s_and_b64 vcc, exec, s[16:17]
	v_cmp_ne_u32_e64 s[4:5], 1, v3
	s_cbranch_vccz .LBB0_907
	s_and_b64 vcc, exec, s[4:5]
	s_cbranch_vccnz .LBB0_907
	s_lshl_b32 s57, s53, 5
	s_add_i32 s92, s57, 0x25800
	v_mov_b32_e32 v232, s92
	ds_read2_b32 v[234:235], v232 offset0:1 offset1:5
	ds_read2_b32 v[236:237], v232 offset0:0 offset1:2
	s_lshl_b32 s89, s53, 11
	s_lshl_b32 s90, s53, 10
	v_lshl_add_u32 v238, v145, 2, s89
	v_lshl_add_u32 v245, v145, 1, s90
	v_add_u32_e32 v238, 0x20000, v238
	v_add_u32_e32 v245, 0x22000, v245
	s_lshl_b32 s60, s53, 9
	s_add_i32 s60, s60, 0x24000
	v_mov_b32_e32 v246, s60
	s_add_i32 s60, s90, 0x24800
	v_mov_b32_e32 v244, s60
	s_waitcnt lgkmcnt(0)
	v_readfirstlane_b32 s91, v234
	v_readfirstlane_b32 s93, v235
	v_readfirstlane_b32 s33, v236
	v_readfirstlane_b32 s90, v237
	s_lshl_b32 s33, s33, 21
	s_add_i32 s60, s93, 63
	s_lshr_b32 s60, s60, 6
	s_cmp_le_u32 s60, 1
	s_cbranch_scc1 .Lref_v1
	s_cmp_le_u32 s60, 2
	s_cbranch_scc1 .Lref_v2
	s_cmp_le_u32 s60, 3
	s_cbranch_scc1 .Lref_v3
	s_cmp_le_u32 s60, 4
	s_cbranch_scc1 .Lref_v4
	s_cmp_le_u32 s60, 5
	s_cbranch_scc1 .Lref_v5
	s_cmp_le_u32 s60, 6
	s_cbranch_scc1 .Lref_v6
	s_cmp_le_u32 s60, 7
	s_cbranch_scc1 .Lref_v7

.Lref_v7:
	ds_read_b32 v216, v238
	ds_read_u16 v224, v245
	ds_read_b32 v217, v238 offset:256
	ds_read_u16 v225, v245 offset:128
	ds_read_b32 v218, v238 offset:512
	ds_read_u16 v226, v245 offset:256
	ds_read_b32 v219, v238 offset:768
	ds_read_u16 v227, v245 offset:384
	ds_read_b32 v220, v238 offset:1024
	ds_read_u16 v228, v245 offset:512
	ds_read_b32 v221, v238 offset:1280
	ds_read_u16 v229, v245 offset:640
	ds_read_b32 v222, v238 offset:1536
	ds_read_u16 v230, v245 offset:768
	v_cmp_gt_u32_e64 s[8:9], s93, v145
	v_add_u32_e32 v241, 64, v145
	v_cmp_gt_u32_e64 s[12:13], s93, v241
	v_add_u32_e32 v241, 128, v145
	v_cmp_gt_u32_e64 s[14:15], s93, v241
	v_add_u32_e32 v241, 192, v145
	v_cmp_gt_u32_e64 s[16:17], s93, v241
	v_add_u32_e32 v241, 256, v145
	v_cmp_gt_u32_e64 s[18:19], s93, v241
	v_add_u32_e32 v241, 320, v145
	v_cmp_gt_u32_e64 s[22:23], s93, v241
	v_add_u32_e32 v241, 384, v145
	v_cmp_gt_u32_e64 s[24:25], s93, v241
	s_waitcnt lgkmcnt(0)
	v_cndmask_b32_e64 v216, 0, v216, s[8:9]
	v_cndmask_b32_e64 v217, 0, v217, s[12:13]
	v_cndmask_b32_e64 v218, 0, v218, s[14:15]
	v_cndmask_b32_e64 v219, 0, v219, s[16:17]
	v_cndmask_b32_e64 v220, 0, v220, s[18:19]
	v_cndmask_b32_e64 v221, 0, v221, s[22:23]
	v_cndmask_b32_e64 v222, 0, v222, s[24:25]
	s_or_b32 s57, s33, 0x100000
	v_cmp_ge_u32_e64 s[8:9], v216, s57
	v_cmp_ge_u32_e64 s[12:13], v217, s57
	v_cmp_ge_u32_e64 s[14:15], v218, s57
	v_cmp_ge_u32_e64 s[16:17], v219, s57
	v_cmp_ge_u32_e64 s[18:19], v220, s57
	v_cmp_ge_u32_e64 s[22:23], v221, s57
	v_cmp_ge_u32_e64 s[24:25], v222, s57
	s_bcnt1_i32_b64 s89, s[8:9]
	s_bcnt1_i32_b64 s61, s[12:13]
	s_add_u32 s89, s89, s61
	s_bcnt1_i32_b64 s61, s[14:15]
	s_add_u32 s89, s89, s61
	s_bcnt1_i32_b64 s61, s[16:17]
	s_add_u32 s89, s89, s61
	s_bcnt1_i32_b64 s61, s[18:19]
	s_add_u32 s89, s89, s61
	s_bcnt1_i32_b64 s61, s[22:23]
	s_add_u32 s89, s89, s61
	s_bcnt1_i32_b64 s61, s[24:25]
	s_add_u32 s89, s89, s61
	s_cmp_ge_u32 s89, s91
	s_cselect_b32 s33, s57, s33
	s_or_b32 s57, s33, 0x80000
	v_cmp_ge_u32_e64 s[8:9], v216, s57
	v_cmp_ge_u32_e64 s[12:13], v217, s57
	v_cmp_ge_u32_e64 s[14:15], v218, s57
	v_cmp_ge_u32_e64 s[16:17], v219, s57
	v_cmp_ge_u32_e64 s[18:19], v220, s57
	v_cmp_ge_u32_e64 s[22:23], v221, s57
	v_cmp_ge_u32_e64 s[24:25], v222, s57
	s_bcnt1_i32_b64 s89, s[8:9]
	s_bcnt1_i32_b64 s61, s[12:13]
	s_add_u32 s89, s89, s61
	s_bcnt1_i32_b64 s61, s[14:15]
	s_add_u32 s89, s89, s61
	s_bcnt1_i32_b64 s61, s[16:17]
	s_add_u32 s89, s89, s61
	s_bcnt1_i32_b64 s61, s[18:19]
	s_add_u32 s89, s89, s61
	s_bcnt1_i32_b64 s61, s[22:23]
	s_add_u32 s89, s89, s61
	s_bcnt1_i32_b64 s61, s[24:25]
	s_add_u32 s89, s89, s61
	s_cmp_ge_u32 s89, s91
	s_cselect_b32 s33, s57, s33
	s_or_b32 s57, s33, 0x40000
	v_cmp_ge_u32_e64 s[8:9], v216, s57
	v_cmp_ge_u32_e64 s[12:13], v217, s57
	v_cmp_ge_u32_e64 s[14:15], v218, s57
	v_cmp_ge_u32_e64 s[16:17], v219, s57
	v_cmp_ge_u32_e64 s[18:19], v220, s57
	v_cmp_ge_u32_e64 s[22:23], v221, s57
	v_cmp_ge_u32_e64 s[24:25], v222, s57
	s_bcnt1_i32_b64 s89, s[8:9]
	s_bcnt1_i32_b64 s61, s[12:13]
	s_add_u32 s89, s89, s61
	s_bcnt1_i32_b64 s61, s[14:15]
	s_add_u32 s89, s89, s61
	s_bcnt1_i32_b64 s61, s[16:17]
	s_add_u32 s89, s89, s61
	s_bcnt1_i32_b64 s61, s[18:19]
	s_add_u32 s89, s89, s61
	s_bcnt1_i32_b64 s61, s[22:23]
	s_add_u32 s89, s89, s61
	s_bcnt1_i32_b64 s61, s[24:25]
	s_add_u32 s89, s89, s61
	s_cmp_ge_u32 s89, s91
	s_cselect_b32 s33, s57, s33
	s_or_b32 s57, s33, 0x20000
	v_cmp_ge_u32_e64 s[8:9], v216, s57
	v_cmp_ge_u32_e64 s[12:13], v217, s57
	v_cmp_ge_u32_e64 s[14:15], v218, s57
	v_cmp_ge_u32_e64 s[16:17], v219, s57
	v_cmp_ge_u32_e64 s[18:19], v220, s57
	v_cmp_ge_u32_e64 s[22:23], v221, s57
	v_cmp_ge_u32_e64 s[24:25], v222, s57
	s_bcnt1_i32_b64 s89, s[8:9]
	s_bcnt1_i32_b64 s61, s[12:13]
	s_add_u32 s89, s89, s61
	s_bcnt1_i32_b64 s61, s[14:15]
	s_add_u32 s89, s89, s61
	s_bcnt1_i32_b64 s61, s[16:17]
	s_add_u32 s89, s89, s61
	s_bcnt1_i32_b64 s61, s[18:19]
	s_add_u32 s89, s89, s61
	s_bcnt1_i32_b64 s61, s[22:23]
	s_add_u32 s89, s89, s61
	s_bcnt1_i32_b64 s61, s[24:25]
	s_add_u32 s89, s89, s61
	s_cmp_ge_u32 s89, s91
	s_cselect_b32 s33, s57, s33
	s_or_b32 s57, s33, 0x10000
	v_cmp_ge_u32_e64 s[8:9], v216, s57
	v_cmp_ge_u32_e64 s[12:13], v217, s57
	v_cmp_ge_u32_e64 s[14:15], v218, s57
	v_cmp_ge_u32_e64 s[16:17], v219, s57
	v_cmp_ge_u32_e64 s[18:19], v220, s57
	v_cmp_ge_u32_e64 s[22:23], v221, s57
	v_cmp_ge_u32_e64 s[24:25], v222, s57
	s_bcnt1_i32_b64 s89, s[8:9]
	s_bcnt1_i32_b64 s61, s[12:13]
	s_add_u32 s89, s89, s61
	s_bcnt1_i32_b64 s61, s[14:15]
	s_add_u32 s89, s89, s61
	s_bcnt1_i32_b64 s61, s[16:17]
	s_add_u32 s89, s89, s61
	s_bcnt1_i32_b64 s61, s[18:19]
	s_add_u32 s89, s89, s61
	s_bcnt1_i32_b64 s61, s[22:23]
	s_add_u32 s89, s89, s61
	s_bcnt1_i32_b64 s61, s[24:25]
	s_add_u32 s89, s89, s61
	s_cmp_ge_u32 s89, s91
	s_cselect_b32 s33, s57, s33
	s_or_b32 s57, s33, 0x8000
	v_cmp_ge_u32_e64 s[8:9], v216, s57
	v_cmp_ge_u32_e64 s[12:13], v217, s57
	v_cmp_ge_u32_e64 s[14:15], v218, s57
	v_cmp_ge_u32_e64 s[16:17], v219, s57
	v_cmp_ge_u32_e64 s[18:19], v220, s57
	v_cmp_ge_u32_e64 s[22:23], v221, s57
	v_cmp_ge_u32_e64 s[24:25], v222, s57
	s_bcnt1_i32_b64 s89, s[8:9]
	s_bcnt1_i32_b64 s61, s[12:13]
	s_add_u32 s89, s89, s61
	s_bcnt1_i32_b64 s61, s[14:15]
	s_add_u32 s89, s89, s61
	s_bcnt1_i32_b64 s61, s[16:17]
	s_add_u32 s89, s89, s61
	s_bcnt1_i32_b64 s61, s[18:19]
	s_add_u32 s89, s89, s61
	s_bcnt1_i32_b64 s61, s[22:23]
	s_add_u32 s89, s89, s61
	s_bcnt1_i32_b64 s61, s[24:25]
	s_add_u32 s89, s89, s61
	s_cmp_ge_u32 s89, s91
	s_cselect_b32 s33, s57, s33
	s_or_b32 s57, s33, 0x4000
	v_cmp_ge_u32_e64 s[8:9], v216, s57
	v_cmp_ge_u32_e64 s[12:13], v217, s57
	v_cmp_ge_u32_e64 s[14:15], v218, s57
	v_cmp_ge_u32_e64 s[16:17], v219, s57
	v_cmp_ge_u32_e64 s[18:19], v220, s57
	v_cmp_ge_u32_e64 s[22:23], v221, s57
	v_cmp_ge_u32_e64 s[24:25], v222, s57
	s_bcnt1_i32_b64 s89, s[8:9]
	s_bcnt1_i32_b64 s61, s[12:13]
	s_add_u32 s89, s89, s61
	s_bcnt1_i32_b64 s61, s[14:15]
	s_add_u32 s89, s89, s61
	s_bcnt1_i32_b64 s61, s[16:17]
	s_add_u32 s89, s89, s61
	s_bcnt1_i32_b64 s61, s[18:19]
	s_add_u32 s89, s89, s61
	s_bcnt1_i32_b64 s61, s[22:23]
	s_add_u32 s89, s89, s61
	s_bcnt1_i32_b64 s61, s[24:25]
	s_add_u32 s89, s89, s61
	s_cmp_ge_u32 s89, s91
	s_cselect_b32 s33, s57, s33
	s_or_b32 s57, s33, 0x2000
	v_cmp_ge_u32_e64 s[8:9], v216, s57
	v_cmp_ge_u32_e64 s[12:13], v217, s57
	v_cmp_ge_u32_e64 s[14:15], v218, s57
	v_cmp_ge_u32_e64 s[16:17], v219, s57
	v_cmp_ge_u32_e64 s[18:19], v220, s57
	v_cmp_ge_u32_e64 s[22:23], v221, s57
	v_cmp_ge_u32_e64 s[24:25], v222, s57
	s_bcnt1_i32_b64 s89, s[8:9]
	s_bcnt1_i32_b64 s61, s[12:13]
	s_add_u32 s89, s89, s61
	s_bcnt1_i32_b64 s61, s[14:15]
	s_add_u32 s89, s89, s61
	s_bcnt1_i32_b64 s61, s[16:17]
	s_add_u32 s89, s89, s61
	s_bcnt1_i32_b64 s61, s[18:19]
	s_add_u32 s89, s89, s61
	s_bcnt1_i32_b64 s61, s[22:23]
	s_add_u32 s89, s89, s61
	s_bcnt1_i32_b64 s61, s[24:25]
	s_add_u32 s89, s89, s61
	s_cmp_ge_u32 s89, s91
	s_cselect_b32 s33, s57, s33
	s_or_b32 s57, s33, 0x1000
	v_cmp_ge_u32_e64 s[8:9], v216, s57
	v_cmp_ge_u32_e64 s[12:13], v217, s57
	v_cmp_ge_u32_e64 s[14:15], v218, s57
	v_cmp_ge_u32_e64 s[16:17], v219, s57
	v_cmp_ge_u32_e64 s[18:19], v220, s57
	v_cmp_ge_u32_e64 s[22:23], v221, s57
	v_cmp_ge_u32_e64 s[24:25], v222, s57
	s_bcnt1_i32_b64 s89, s[8:9]
	s_bcnt1_i32_b64 s61, s[12:13]
	s_add_u32 s89, s89, s61
	s_bcnt1_i32_b64 s61, s[14:15]
	s_add_u32 s89, s89, s61
	s_bcnt1_i32_b64 s61, s[16:17]
	s_add_u32 s89, s89, s61
	s_bcnt1_i32_b64 s61, s[18:19]
	s_add_u32 s89, s89, s61
	s_bcnt1_i32_b64 s61, s[22:23]
	s_add_u32 s89, s89, s61
	s_bcnt1_i32_b64 s61, s[24:25]
	s_add_u32 s89, s89, s61
	s_cmp_ge_u32 s89, s91
	s_cselect_b32 s33, s57, s33
	s_or_b32 s57, s33, 0x800
	v_cmp_ge_u32_e64 s[8:9], v216, s57
	v_cmp_ge_u32_e64 s[12:13], v217, s57
	v_cmp_ge_u32_e64 s[14:15], v218, s57
	v_cmp_ge_u32_e64 s[16:17], v219, s57
	v_cmp_ge_u32_e64 s[18:19], v220, s57
	v_cmp_ge_u32_e64 s[22:23], v221, s57
	v_cmp_ge_u32_e64 s[24:25], v222, s57
	s_bcnt1_i32_b64 s89, s[8:9]
	s_bcnt1_i32_b64 s61, s[12:13]
	s_add_u32 s89, s89, s61
	s_bcnt1_i32_b64 s61, s[14:15]
	s_add_u32 s89, s89, s61
	s_bcnt1_i32_b64 s61, s[16:17]
	s_add_u32 s89, s89, s61
	s_bcnt1_i32_b64 s61, s[18:19]
	s_add_u32 s89, s89, s61
	s_bcnt1_i32_b64 s61, s[22:23]
	s_add_u32 s89, s89, s61
	s_bcnt1_i32_b64 s61, s[24:25]
	s_add_u32 s89, s89, s61
	s_cmp_ge_u32 s89, s91
	s_cselect_b32 s33, s57, s33
	s_or_b32 s57, s33, 0x400
	v_cmp_ge_u32_e64 s[8:9], v216, s57
	v_cmp_ge_u32_e64 s[12:13], v217, s57
	v_cmp_ge_u32_e64 s[14:15], v218, s57
	v_cmp_ge_u32_e64 s[16:17], v219, s57
	v_cmp_ge_u32_e64 s[18:19], v220, s57
	v_cmp_ge_u32_e64 s[22:23], v221, s57
	v_cmp_ge_u32_e64 s[24:25], v222, s57
	s_bcnt1_i32_b64 s89, s[8:9]
	s_bcnt1_i32_b64 s61, s[12:13]
	s_add_u32 s89, s89, s61
	s_bcnt1_i32_b64 s61, s[14:15]
	s_add_u32 s89, s89, s61
	s_bcnt1_i32_b64 s61, s[16:17]
	s_add_u32 s89, s89, s61
	s_bcnt1_i32_b64 s61, s[18:19]
	s_add_u32 s89, s89, s61
	s_bcnt1_i32_b64 s61, s[22:23]
	s_add_u32 s89, s89, s61
	s_bcnt1_i32_b64 s61, s[24:25]
	s_add_u32 s89, s89, s61
	s_cmp_ge_u32 s89, s91
	s_cselect_b32 s33, s57, s33
	s_or_b32 s57, s33, 0x200
	v_cmp_ge_u32_e64 s[8:9], v216, s57
	v_cmp_ge_u32_e64 s[12:13], v217, s57
	v_cmp_ge_u32_e64 s[14:15], v218, s57
	v_cmp_ge_u32_e64 s[16:17], v219, s57
	v_cmp_ge_u32_e64 s[18:19], v220, s57
	v_cmp_ge_u32_e64 s[22:23], v221, s57
	v_cmp_ge_u32_e64 s[24:25], v222, s57
	s_bcnt1_i32_b64 s89, s[8:9]
	s_bcnt1_i32_b64 s61, s[12:13]
	s_add_u32 s89, s89, s61
	s_bcnt1_i32_b64 s61, s[14:15]
	s_add_u32 s89, s89, s61
	s_bcnt1_i32_b64 s61, s[16:17]
	s_add_u32 s89, s89, s61
	s_bcnt1_i32_b64 s61, s[18:19]
	s_add_u32 s89, s89, s61
	s_bcnt1_i32_b64 s61, s[22:23]
	s_add_u32 s89, s89, s61
	s_bcnt1_i32_b64 s61, s[24:25]
	s_add_u32 s89, s89, s61
	s_cmp_ge_u32 s89, s91
	s_cselect_b32 s33, s57, s33
	s_or_b32 s57, s33, 0x100
	v_cmp_ge_u32_e64 s[8:9], v216, s57
	v_cmp_ge_u32_e64 s[12:13], v217, s57
	v_cmp_ge_u32_e64 s[14:15], v218, s57
	v_cmp_ge_u32_e64 s[16:17], v219, s57
	v_cmp_ge_u32_e64 s[18:19], v220, s57
	v_cmp_ge_u32_e64 s[22:23], v221, s57
	v_cmp_ge_u32_e64 s[24:25], v222, s57
	s_bcnt1_i32_b64 s89, s[8:9]
	s_bcnt1_i32_b64 s61, s[12:13]
	s_add_u32 s89, s89, s61
	s_bcnt1_i32_b64 s61, s[14:15]
	s_add_u32 s89, s89, s61
	s_bcnt1_i32_b64 s61, s[16:17]
	s_add_u32 s89, s89, s61
	s_bcnt1_i32_b64 s61, s[18:19]
	s_add_u32 s89, s89, s61
	s_bcnt1_i32_b64 s61, s[22:23]
	s_add_u32 s89, s89, s61
	s_bcnt1_i32_b64 s61, s[24:25]
	s_add_u32 s89, s89, s61
	s_cmp_ge_u32 s89, s91
	s_cselect_b32 s33, s57, s33
	s_or_b32 s57, s33, 0x80
	v_cmp_ge_u32_e64 s[8:9], v216, s57
	v_cmp_ge_u32_e64 s[12:13], v217, s57
	v_cmp_ge_u32_e64 s[14:15], v218, s57
	v_cmp_ge_u32_e64 s[16:17], v219, s57
	v_cmp_ge_u32_e64 s[18:19], v220, s57
	v_cmp_ge_u32_e64 s[22:23], v221, s57
	v_cmp_ge_u32_e64 s[24:25], v222, s57
	s_bcnt1_i32_b64 s89, s[8:9]
	s_bcnt1_i32_b64 s61, s[12:13]
	s_add_u32 s89, s89, s61
	s_bcnt1_i32_b64 s61, s[14:15]
	s_add_u32 s89, s89, s61
	s_bcnt1_i32_b64 s61, s[16:17]
	s_add_u32 s89, s89, s61
	s_bcnt1_i32_b64 s61, s[18:19]
	s_add_u32 s89, s89, s61
	s_bcnt1_i32_b64 s61, s[22:23]
	s_add_u32 s89, s89, s61
	s_bcnt1_i32_b64 s61, s[24:25]
	s_add_u32 s89, s89, s61
	s_cmp_ge_u32 s89, s91
	s_cselect_b32 s33, s57, s33
	s_or_b32 s57, s33, 0x40
	v_cmp_ge_u32_e64 s[8:9], v216, s57
	v_cmp_ge_u32_e64 s[12:13], v217, s57
	v_cmp_ge_u32_e64 s[14:15], v218, s57
	v_cmp_ge_u32_e64 s[16:17], v219, s57
	v_cmp_ge_u32_e64 s[18:19], v220, s57
	v_cmp_ge_u32_e64 s[22:23], v221, s57
	v_cmp_ge_u32_e64 s[24:25], v222, s57
	s_bcnt1_i32_b64 s89, s[8:9]
	s_bcnt1_i32_b64 s61, s[12:13]
	s_add_u32 s89, s89, s61
	s_bcnt1_i32_b64 s61, s[14:15]
	s_add_u32 s89, s89, s61
	s_bcnt1_i32_b64 s61, s[16:17]
	s_add_u32 s89, s89, s61
	s_bcnt1_i32_b64 s61, s[18:19]
	s_add_u32 s89, s89, s61
	s_bcnt1_i32_b64 s61, s[22:23]
	s_add_u32 s89, s89, s61
	s_bcnt1_i32_b64 s61, s[24:25]
	s_add_u32 s89, s89, s61
	s_cmp_ge_u32 s89, s91
	s_cselect_b32 s33, s57, s33
	s_or_b32 s57, s33, 0x20
	v_cmp_ge_u32_e64 s[8:9], v216, s57
	v_cmp_ge_u32_e64 s[12:13], v217, s57
	v_cmp_ge_u32_e64 s[14:15], v218, s57
	v_cmp_ge_u32_e64 s[16:17], v219, s57
	v_cmp_ge_u32_e64 s[18:19], v220, s57
	v_cmp_ge_u32_e64 s[22:23], v221, s57
	v_cmp_ge_u32_e64 s[24:25], v222, s57
	s_bcnt1_i32_b64 s89, s[8:9]
	s_bcnt1_i32_b64 s61, s[12:13]
	s_add_u32 s89, s89, s61
	s_bcnt1_i32_b64 s61, s[14:15]
	s_add_u32 s89, s89, s61
	s_bcnt1_i32_b64 s61, s[16:17]
	s_add_u32 s89, s89, s61
	s_bcnt1_i32_b64 s61, s[18:19]
	s_add_u32 s89, s89, s61
	s_bcnt1_i32_b64 s61, s[22:23]
	s_add_u32 s89, s89, s61
	s_bcnt1_i32_b64 s61, s[24:25]
	s_add_u32 s89, s89, s61
	s_cmp_ge_u32 s89, s91
	s_cselect_b32 s33, s57, s33
	s_or_b32 s57, s33, 0x10
	v_cmp_ge_u32_e64 s[8:9], v216, s57
	v_cmp_ge_u32_e64 s[12:13], v217, s57
	v_cmp_ge_u32_e64 s[14:15], v218, s57
	v_cmp_ge_u32_e64 s[16:17], v219, s57
	v_cmp_ge_u32_e64 s[18:19], v220, s57
	v_cmp_ge_u32_e64 s[22:23], v221, s57
	v_cmp_ge_u32_e64 s[24:25], v222, s57
	s_bcnt1_i32_b64 s89, s[8:9]
	s_bcnt1_i32_b64 s61, s[12:13]
	s_add_u32 s89, s89, s61
	s_bcnt1_i32_b64 s61, s[14:15]
	s_add_u32 s89, s89, s61
	s_bcnt1_i32_b64 s61, s[16:17]
	s_add_u32 s89, s89, s61
	s_bcnt1_i32_b64 s61, s[18:19]
	s_add_u32 s89, s89, s61
	s_bcnt1_i32_b64 s61, s[22:23]
	s_add_u32 s89, s89, s61
	s_bcnt1_i32_b64 s61, s[24:25]
	s_add_u32 s89, s89, s61
	s_cmp_ge_u32 s89, s91
	s_cselect_b32 s33, s57, s33
	s_or_b32 s57, s33, 0x8
	v_cmp_ge_u32_e64 s[8:9], v216, s57
	v_cmp_ge_u32_e64 s[12:13], v217, s57
	v_cmp_ge_u32_e64 s[14:15], v218, s57
	v_cmp_ge_u32_e64 s[16:17], v219, s57
	v_cmp_ge_u32_e64 s[18:19], v220, s57
	v_cmp_ge_u32_e64 s[22:23], v221, s57
	v_cmp_ge_u32_e64 s[24:25], v222, s57
	s_bcnt1_i32_b64 s89, s[8:9]
	s_bcnt1_i32_b64 s61, s[12:13]
	s_add_u32 s89, s89, s61
	s_bcnt1_i32_b64 s61, s[14:15]
	s_add_u32 s89, s89, s61
	s_bcnt1_i32_b64 s61, s[16:17]
	s_add_u32 s89, s89, s61
	s_bcnt1_i32_b64 s61, s[18:19]
	s_add_u32 s89, s89, s61
	s_bcnt1_i32_b64 s61, s[22:23]
	s_add_u32 s89, s89, s61
	s_bcnt1_i32_b64 s61, s[24:25]
	s_add_u32 s89, s89, s61
	s_cmp_ge_u32 s89, s91
	s_cselect_b32 s33, s57, s33
	s_or_b32 s57, s33, 0x4
	v_cmp_ge_u32_e64 s[8:9], v216, s57
	v_cmp_ge_u32_e64 s[12:13], v217, s57
	v_cmp_ge_u32_e64 s[14:15], v218, s57
	v_cmp_ge_u32_e64 s[16:17], v219, s57
	v_cmp_ge_u32_e64 s[18:19], v220, s57
	v_cmp_ge_u32_e64 s[22:23], v221, s57
	v_cmp_ge_u32_e64 s[24:25], v222, s57
	s_bcnt1_i32_b64 s89, s[8:9]
	s_bcnt1_i32_b64 s61, s[12:13]
	s_add_u32 s89, s89, s61
	s_bcnt1_i32_b64 s61, s[14:15]
	s_add_u32 s89, s89, s61
	s_bcnt1_i32_b64 s61, s[16:17]
	s_add_u32 s89, s89, s61
	s_bcnt1_i32_b64 s61, s[18:19]
	s_add_u32 s89, s89, s61
	s_bcnt1_i32_b64 s61, s[22:23]
	s_add_u32 s89, s89, s61
	s_bcnt1_i32_b64 s61, s[24:25]
	s_add_u32 s89, s89, s61
	s_cmp_ge_u32 s89, s91
	s_cselect_b32 s33, s57, s33
	s_or_b32 s57, s33, 0x2
	v_cmp_ge_u32_e64 s[8:9], v216, s57
	v_cmp_ge_u32_e64 s[12:13], v217, s57
	v_cmp_ge_u32_e64 s[14:15], v218, s57
	v_cmp_ge_u32_e64 s[16:17], v219, s57
	v_cmp_ge_u32_e64 s[18:19], v220, s57
	v_cmp_ge_u32_e64 s[22:23], v221, s57
	v_cmp_ge_u32_e64 s[24:25], v222, s57
	s_bcnt1_i32_b64 s89, s[8:9]
	s_bcnt1_i32_b64 s61, s[12:13]
	s_add_u32 s89, s89, s61
	s_bcnt1_i32_b64 s61, s[14:15]
	s_add_u32 s89, s89, s61
	s_bcnt1_i32_b64 s61, s[16:17]
	s_add_u32 s89, s89, s61
	s_bcnt1_i32_b64 s61, s[18:19]
	s_add_u32 s89, s89, s61
	s_bcnt1_i32_b64 s61, s[22:23]
	s_add_u32 s89, s89, s61
	s_bcnt1_i32_b64 s61, s[24:25]
	s_add_u32 s89, s89, s61
	s_cmp_ge_u32 s89, s91
	s_cselect_b32 s33, s57, s33
	s_or_b32 s57, s33, 0x1
	v_cmp_ge_u32_e64 s[8:9], v216, s57
	v_cmp_ge_u32_e64 s[12:13], v217, s57
	v_cmp_ge_u32_e64 s[14:15], v218, s57
	v_cmp_ge_u32_e64 s[16:17], v219, s57
	v_cmp_ge_u32_e64 s[18:19], v220, s57
	v_cmp_ge_u32_e64 s[22:23], v221, s57
	v_cmp_ge_u32_e64 s[24:25], v222, s57
	s_bcnt1_i32_b64 s89, s[8:9]
	s_bcnt1_i32_b64 s61, s[12:13]
	s_add_u32 s89, s89, s61
	s_bcnt1_i32_b64 s61, s[14:15]
	s_add_u32 s89, s89, s61
	s_bcnt1_i32_b64 s61, s[16:17]
	s_add_u32 s89, s89, s61
	s_bcnt1_i32_b64 s61, s[18:19]
	s_add_u32 s89, s89, s61
	s_bcnt1_i32_b64 s61, s[22:23]
	s_add_u32 s89, s89, s61
	s_bcnt1_i32_b64 s61, s[24:25]
	s_add_u32 s89, s89, s61
	s_cmp_ge_u32 s89, s91
	s_cselect_b32 s33, s57, s33
	v_cmp_gt_u32_e64 s[8:9], v216, s33
	v_cmp_gt_u32_e64 s[12:13], v217, s33
	v_cmp_gt_u32_e64 s[14:15], v218, s33
	v_cmp_gt_u32_e64 s[16:17], v219, s33
	v_cmp_gt_u32_e64 s[18:19], v220, s33
	v_cmp_gt_u32_e64 s[22:23], v221, s33
	v_cmp_gt_u32_e64 s[24:25], v222, s33
	s_bcnt1_i32_b64 s89, s[8:9]
	s_bcnt1_i32_b64 s61, s[12:13]
	s_add_u32 s89, s89, s61
	s_bcnt1_i32_b64 s61, s[14:15]
	s_add_u32 s89, s89, s61
	s_bcnt1_i32_b64 s61, s[16:17]
	s_add_u32 s89, s89, s61
	s_bcnt1_i32_b64 s61, s[18:19]
	s_add_u32 s89, s89, s61
	s_bcnt1_i32_b64 s61, s[22:23]
	s_add_u32 s89, s89, s61
	s_bcnt1_i32_b64 s61, s[24:25]
	s_add_u32 s89, s89, s61
	s_sub_u32 s91, s91, s89
	v_cmp_eq_u32_e64 s[8:9], v216, s33
	v_cmp_eq_u32_e64 s[12:13], v217, s33
	v_cmp_eq_u32_e64 s[14:15], v218, s33
	v_cmp_eq_u32_e64 s[16:17], v219, s33
	v_cmp_eq_u32_e64 s[18:19], v220, s33
	v_cmp_eq_u32_e64 s[22:23], v221, s33
	v_cmp_eq_u32_e64 s[24:25], v222, s33
	s_bcnt1_i32_b64 s89, s[8:9]
	s_bcnt1_i32_b64 s61, s[12:13]
	s_add_u32 s89, s89, s61
	s_bcnt1_i32_b64 s61, s[14:15]
	s_add_u32 s89, s89, s61
	s_bcnt1_i32_b64 s61, s[16:17]
	s_add_u32 s89, s89, s61
	s_bcnt1_i32_b64 s61, s[18:19]
	s_add_u32 s89, s89, s61
	s_bcnt1_i32_b64 s61, s[22:23]
	s_add_u32 s89, s89, s61
	s_bcnt1_i32_b64 s61, s[24:25]
	s_add_u32 s89, s89, s61
	s_add_u32 s57, s33, 1
	s_cmp_eq_u32 s91, s89
	s_cselect_b32 s57, s33, s57
	s_cselect_b32 s60, 1, 0
	v_cmp_ge_u32_e64 s[8:9], v216, s57
	v_cmp_ge_u32_e64 s[12:13], v217, s57
	v_cmp_ge_u32_e64 s[14:15], v218, s57
	v_cmp_ge_u32_e64 s[16:17], v219, s57
	v_cmp_ge_u32_e64 s[18:19], v220, s57
	v_cmp_ge_u32_e64 s[22:23], v221, s57
	v_cmp_ge_u32_e64 s[24:25], v222, s57
	s_nop 1
	v_mbcnt_lo_u32_b32 v241, s8, 0
	v_mbcnt_hi_u32_b32 v241, s9, v241
	v_add_u32_e32 v241, s90, v241
	v_and_b32_e32 v241, 0xff, v241
	v_lshl_add_u32 v241, v241, 1, v246
	s_mov_b64 exec, s[8:9]
	ds_write_b16 v241, v224
	s_mov_b64 exec, -1
	s_bcnt1_i32_b64 s61, s[8:9]
	s_add_u32 s90, s90, s61
	v_mbcnt_lo_u32_b32 v241, s12, 0
	v_mbcnt_hi_u32_b32 v241, s13, v241
	v_add_u32_e32 v241, s90, v241
	v_and_b32_e32 v241, 0xff, v241
	v_lshl_add_u32 v241, v241, 1, v246
	s_mov_b64 exec, s[12:13]
	ds_write_b16 v241, v225
	s_mov_b64 exec, -1
	s_bcnt1_i32_b64 s61, s[12:13]
	s_add_u32 s90, s90, s61
	v_mbcnt_lo_u32_b32 v241, s14, 0
	v_mbcnt_hi_u32_b32 v241, s15, v241
	v_add_u32_e32 v241, s90, v241
	v_and_b32_e32 v241, 0xff, v241
	v_lshl_add_u32 v241, v241, 1, v246
	s_mov_b64 exec, s[14:15]
	ds_write_b16 v241, v226
	s_mov_b64 exec, -1
	s_bcnt1_i32_b64 s61, s[14:15]
	s_add_u32 s90, s90, s61
	v_mbcnt_lo_u32_b32 v241, s16, 0
	v_mbcnt_hi_u32_b32 v241, s17, v241
	v_add_u32_e32 v241, s90, v241
	v_and_b32_e32 v241, 0xff, v241
	v_lshl_add_u32 v241, v241, 1, v246
	s_mov_b64 exec, s[16:17]
	ds_write_b16 v241, v227
	s_mov_b64 exec, -1
	s_bcnt1_i32_b64 s61, s[16:17]
	s_add_u32 s90, s90, s61
	v_mbcnt_lo_u32_b32 v241, s18, 0
	v_mbcnt_hi_u32_b32 v241, s19, v241
	v_add_u32_e32 v241, s90, v241
	v_and_b32_e32 v241, 0xff, v241
	v_lshl_add_u32 v241, v241, 1, v246
	s_mov_b64 exec, s[18:19]
	ds_write_b16 v241, v228
	s_mov_b64 exec, -1
	s_bcnt1_i32_b64 s61, s[18:19]
	s_add_u32 s90, s90, s61
	v_mbcnt_lo_u32_b32 v241, s22, 0
	v_mbcnt_hi_u32_b32 v241, s23, v241
	v_add_u32_e32 v241, s90, v241
	v_and_b32_e32 v241, 0xff, v241
	v_lshl_add_u32 v241, v241, 1, v246
	s_mov_b64 exec, s[22:23]
	ds_write_b16 v241, v229
	s_mov_b64 exec, -1
	s_bcnt1_i32_b64 s61, s[22:23]
	s_add_u32 s90, s90, s61
	v_mbcnt_lo_u32_b32 v241, s24, 0
	v_mbcnt_hi_u32_b32 v241, s25, v241
	v_add_u32_e32 v241, s90, v241
	v_and_b32_e32 v241, 0xff, v241
	v_lshl_add_u32 v241, v241, 1, v246
	s_mov_b64 exec, s[24:25]
	ds_write_b16 v241, v230
	s_mov_b64 exec, -1
	s_bcnt1_i32_b64 s61, s[24:25]
	s_add_u32 s90, s90, s61
	s_mov_b32 s92, 0
	s_cmp_lg_u32 s60, 0
	s_cbranch_scc1 .Lref_fin
	v_cmp_eq_u32_e64 s[8:9], v216, s33
	v_cmp_eq_u32_e64 s[12:13], v217, s33
	v_cmp_eq_u32_e64 s[14:15], v218, s33
	v_cmp_eq_u32_e64 s[16:17], v219, s33
	v_cmp_eq_u32_e64 s[18:19], v220, s33
	v_cmp_eq_u32_e64 s[22:23], v221, s33
	v_cmp_eq_u32_e64 s[24:25], v222, s33
	s_nop 1
	v_mbcnt_lo_u32_b32 v241, s8, 0
	v_mbcnt_hi_u32_b32 v241, s9, v241
	v_add_u32_e32 v241, s92, v241
	v_lshl_add_u32 v241, v241, 1, v244
	s_mov_b64 exec, s[8:9]
	ds_write_b16 v241, v224
	s_mov_b64 exec, -1
	s_bcnt1_i32_b64 s61, s[8:9]
	s_add_u32 s92, s92, s61
	v_mbcnt_lo_u32_b32 v241, s12, 0
	v_mbcnt_hi_u32_b32 v241, s13, v241
	v_add_u32_e32 v241, s92, v241
	v_lshl_add_u32 v241, v241, 1, v244
	s_mov_b64 exec, s[12:13]
	ds_write_b16 v241, v225
	s_mov_b64 exec, -1
	s_bcnt1_i32_b64 s61, s[12:13]
	s_add_u32 s92, s92, s61
	v_mbcnt_lo_u32_b32 v241, s14, 0
	v_mbcnt_hi_u32_b32 v241, s15, v241
	v_add_u32_e32 v241, s92, v241
	v_lshl_add_u32 v241, v241, 1, v244
	s_mov_b64 exec, s[14:15]
	ds_write_b16 v241, v226
	s_mov_b64 exec, -1
	s_bcnt1_i32_b64 s61, s[14:15]
	s_add_u32 s92, s92, s61
	v_mbcnt_lo_u32_b32 v241, s16, 0
	v_mbcnt_hi_u32_b32 v241, s17, v241
	v_add_u32_e32 v241, s92, v241
	v_lshl_add_u32 v241, v241, 1, v244
	s_mov_b64 exec, s[16:17]
	ds_write_b16 v241, v227
	s_mov_b64 exec, -1
	s_bcnt1_i32_b64 s61, s[16:17]
	s_add_u32 s92, s92, s61
	v_mbcnt_lo_u32_b32 v241, s18, 0
	v_mbcnt_hi_u32_b32 v241, s19, v241
	v_add_u32_e32 v241, s92, v241
	v_lshl_add_u32 v241, v241, 1, v244
	s_mov_b64 exec, s[18:19]
	ds_write_b16 v241, v228
	s_mov_b64 exec, -1
	s_bcnt1_i32_b64 s61, s[18:19]
	s_add_u32 s92, s92, s61
	v_mbcnt_lo_u32_b32 v241, s22, 0
	v_mbcnt_hi_u32_b32 v241, s23, v241
	v_add_u32_e32 v241, s92, v241
	v_lshl_add_u32 v241, v241, 1, v244
	s_mov_b64 exec, s[22:23]
	ds_write_b16 v241, v229
	s_mov_b64 exec, -1
	s_bcnt1_i32_b64 s61, s[22:23]
	s_add_u32 s92, s92, s61
	v_mbcnt_lo_u32_b32 v241, s24, 0
	v_mbcnt_hi_u32_b32 v241, s25, v241
	v_add_u32_e32 v241, s92, v241
	v_lshl_add_u32 v241, v241, 1, v244
	s_mov_b64 exec, s[24:25]
	ds_write_b16 v241, v230
	s_mov_b64 exec, -1
	s_bcnt1_i32_b64 s61, s[24:25]
	s_add_u32 s92, s92, s61
	s_branch .Lref_fin
.Lref_v6:
	ds_read_b32 v216, v238
	ds_read_u16 v224, v245
	ds_read_b32 v217, v238 offset:256
	ds_read_u16 v225, v245 offset:128
	ds_read_b32 v218, v238 offset:512
	ds_read_u16 v226, v245 offset:256
	ds_read_b32 v219, v238 offset:768
	ds_read_u16 v227, v245 offset:384
	ds_read_b32 v220, v238 offset:1024
	ds_read_u16 v228, v245 offset:512
	ds_read_b32 v221, v238 offset:1280
	ds_read_u16 v229, v245 offset:640
	v_cmp_gt_u32_e64 s[8:9], s93, v145
	v_add_u32_e32 v241, 64, v145
	v_cmp_gt_u32_e64 s[12:13], s93, v241
	v_add_u32_e32 v241, 128, v145
	v_cmp_gt_u32_e64 s[14:15], s93, v241
	v_add_u32_e32 v241, 192, v145
	v_cmp_gt_u32_e64 s[16:17], s93, v241
	v_add_u32_e32 v241, 256, v145
	v_cmp_gt_u32_e64 s[18:19], s93, v241
	v_add_u32_e32 v241, 320, v145
	v_cmp_gt_u32_e64 s[22:23], s93, v241
	s_waitcnt lgkmcnt(0)
	v_cndmask_b32_e64 v216, 0, v216, s[8:9]
	v_cndmask_b32_e64 v217, 0, v217, s[12:13]
	v_cndmask_b32_e64 v218, 0, v218, s[14:15]
	v_cndmask_b32_e64 v219, 0, v219, s[16:17]
	v_cndmask_b32_e64 v220, 0, v220, s[18:19]
	v_cndmask_b32_e64 v221, 0, v221, s[22:23]
	s_or_b32 s57, s33, 0x100000
	v_cmp_ge_u32_e64 s[8:9], v216, s57
	v_cmp_ge_u32_e64 s[12:13], v217, s57
	v_cmp_ge_u32_e64 s[14:15], v218, s57
	v_cmp_ge_u32_e64 s[16:17], v219, s57
	v_cmp_ge_u32_e64 s[18:19], v220, s57
	v_cmp_ge_u32_e64 s[22:23], v221, s57
	s_bcnt1_i32_b64 s89, s[8:9]
	s_bcnt1_i32_b64 s61, s[12:13]
	s_add_u32 s89, s89, s61
	s_bcnt1_i32_b64 s61, s[14:15]
	s_add_u32 s89, s89, s61
	s_bcnt1_i32_b64 s61, s[16:17]
	s_add_u32 s89, s89, s61
	s_bcnt1_i32_b64 s61, s[18:19]
	s_add_u32 s89, s89, s61
	s_bcnt1_i32_b64 s61, s[22:23]
	s_add_u32 s89, s89, s61
	s_cmp_ge_u32 s89, s91
	s_cselect_b32 s33, s57, s33
	s_or_b32 s57, s33, 0x80000
	v_cmp_ge_u32_e64 s[8:9], v216, s57
	v_cmp_ge_u32_e64 s[12:13], v217, s57
	v_cmp_ge_u32_e64 s[14:15], v218, s57
	v_cmp_ge_u32_e64 s[16:17], v219, s57
	v_cmp_ge_u32_e64 s[18:19], v220, s57
	v_cmp_ge_u32_e64 s[22:23], v221, s57
	s_bcnt1_i32_b64 s89, s[8:9]
	s_bcnt1_i32_b64 s61, s[12:13]
	s_add_u32 s89, s89, s61
	s_bcnt1_i32_b64 s61, s[14:15]
	s_add_u32 s89, s89, s61
	s_bcnt1_i32_b64 s61, s[16:17]
	s_add_u32 s89, s89, s61
	s_bcnt1_i32_b64 s61, s[18:19]
	s_add_u32 s89, s89, s61
	s_bcnt1_i32_b64 s61, s[22:23]
	s_add_u32 s89, s89, s61
	s_cmp_ge_u32 s89, s91
	s_cselect_b32 s33, s57, s33
	s_or_b32 s57, s33, 0x40000
	v_cmp_ge_u32_e64 s[8:9], v216, s57
	v_cmp_ge_u32_e64 s[12:13], v217, s57
	v_cmp_ge_u32_e64 s[14:15], v218, s57
	v_cmp_ge_u32_e64 s[16:17], v219, s57
	v_cmp_ge_u32_e64 s[18:19], v220, s57
	v_cmp_ge_u32_e64 s[22:23], v221, s57
	s_bcnt1_i32_b64 s89, s[8:9]
	s_bcnt1_i32_b64 s61, s[12:13]
	s_add_u32 s89, s89, s61
	s_bcnt1_i32_b64 s61, s[14:15]
	s_add_u32 s89, s89, s61
	s_bcnt1_i32_b64 s61, s[16:17]
	s_add_u32 s89, s89, s61
	s_bcnt1_i32_b64 s61, s[18:19]
	s_add_u32 s89, s89, s61
	s_bcnt1_i32_b64 s61, s[22:23]
	s_add_u32 s89, s89, s61
	s_cmp_ge_u32 s89, s91
	s_cselect_b32 s33, s57, s33
	s_or_b32 s57, s33, 0x20000
	v_cmp_ge_u32_e64 s[8:9], v216, s57
	v_cmp_ge_u32_e64 s[12:13], v217, s57
	v_cmp_ge_u32_e64 s[14:15], v218, s57
	v_cmp_ge_u32_e64 s[16:17], v219, s57
	v_cmp_ge_u32_e64 s[18:19], v220, s57
	v_cmp_ge_u32_e64 s[22:23], v221, s57
	s_bcnt1_i32_b64 s89, s[8:9]
	s_bcnt1_i32_b64 s61, s[12:13]
	s_add_u32 s89, s89, s61
	s_bcnt1_i32_b64 s61, s[14:15]
	s_add_u32 s89, s89, s61
	s_bcnt1_i32_b64 s61, s[16:17]
	s_add_u32 s89, s89, s61
	s_bcnt1_i32_b64 s61, s[18:19]
	s_add_u32 s89, s89, s61
	s_bcnt1_i32_b64 s61, s[22:23]
	s_add_u32 s89, s89, s61
	s_cmp_ge_u32 s89, s91
	s_cselect_b32 s33, s57, s33
	s_or_b32 s57, s33, 0x10000
	v_cmp_ge_u32_e64 s[8:9], v216, s57
	v_cmp_ge_u32_e64 s[12:13], v217, s57
	v_cmp_ge_u32_e64 s[14:15], v218, s57
	v_cmp_ge_u32_e64 s[16:17], v219, s57
	v_cmp_ge_u32_e64 s[18:19], v220, s57
	v_cmp_ge_u32_e64 s[22:23], v221, s57
	s_bcnt1_i32_b64 s89, s[8:9]
	s_bcnt1_i32_b64 s61, s[12:13]
	s_add_u32 s89, s89, s61
	s_bcnt1_i32_b64 s61, s[14:15]
	s_add_u32 s89, s89, s61
	s_bcnt1_i32_b64 s61, s[16:17]
	s_add_u32 s89, s89, s61
	s_bcnt1_i32_b64 s61, s[18:19]
	s_add_u32 s89, s89, s61
	s_bcnt1_i32_b64 s61, s[22:23]
	s_add_u32 s89, s89, s61
	s_cmp_ge_u32 s89, s91
	s_cselect_b32 s33, s57, s33
	s_or_b32 s57, s33, 0x8000
	v_cmp_ge_u32_e64 s[8:9], v216, s57
	v_cmp_ge_u32_e64 s[12:13], v217, s57
	v_cmp_ge_u32_e64 s[14:15], v218, s57
	v_cmp_ge_u32_e64 s[16:17], v219, s57
	v_cmp_ge_u32_e64 s[18:19], v220, s57
	v_cmp_ge_u32_e64 s[22:23], v221, s57
	s_bcnt1_i32_b64 s89, s[8:9]
	s_bcnt1_i32_b64 s61, s[12:13]
	s_add_u32 s89, s89, s61
	s_bcnt1_i32_b64 s61, s[14:15]
	s_add_u32 s89, s89, s61
	s_bcnt1_i32_b64 s61, s[16:17]
	s_add_u32 s89, s89, s61
	s_bcnt1_i32_b64 s61, s[18:19]
	s_add_u32 s89, s89, s61
	s_bcnt1_i32_b64 s61, s[22:23]
	s_add_u32 s89, s89, s61
	s_cmp_ge_u32 s89, s91
	s_cselect_b32 s33, s57, s33
	s_or_b32 s57, s33, 0x4000
	v_cmp_ge_u32_e64 s[8:9], v216, s57
	v_cmp_ge_u32_e64 s[12:13], v217, s57
	v_cmp_ge_u32_e64 s[14:15], v218, s57
	v_cmp_ge_u32_e64 s[16:17], v219, s57
	v_cmp_ge_u32_e64 s[18:19], v220, s57
	v_cmp_ge_u32_e64 s[22:23], v221, s57
	s_bcnt1_i32_b64 s89, s[8:9]
	s_bcnt1_i32_b64 s61, s[12:13]
	s_add_u32 s89, s89, s61
	s_bcnt1_i32_b64 s61, s[14:15]
	s_add_u32 s89, s89, s61
	s_bcnt1_i32_b64 s61, s[16:17]
	s_add_u32 s89, s89, s61
	s_bcnt1_i32_b64 s61, s[18:19]
	s_add_u32 s89, s89, s61
	s_bcnt1_i32_b64 s61, s[22:23]
	s_add_u32 s89, s89, s61
	s_cmp_ge_u32 s89, s91
	s_cselect_b32 s33, s57, s33
	s_or_b32 s57, s33, 0x2000
	v_cmp_ge_u32_e64 s[8:9], v216, s57
	v_cmp_ge_u32_e64 s[12:13], v217, s57
	v_cmp_ge_u32_e64 s[14:15], v218, s57
	v_cmp_ge_u32_e64 s[16:17], v219, s57
	v_cmp_ge_u32_e64 s[18:19], v220, s57
	v_cmp_ge_u32_e64 s[22:23], v221, s57
	s_bcnt1_i32_b64 s89, s[8:9]
	s_bcnt1_i32_b64 s61, s[12:13]
	s_add_u32 s89, s89, s61
	s_bcnt1_i32_b64 s61, s[14:15]
	s_add_u32 s89, s89, s61
	s_bcnt1_i32_b64 s61, s[16:17]
	s_add_u32 s89, s89, s61
	s_bcnt1_i32_b64 s61, s[18:19]
	s_add_u32 s89, s89, s61
	s_bcnt1_i32_b64 s61, s[22:23]
	s_add_u32 s89, s89, s61
	s_cmp_ge_u32 s89, s91
	s_cselect_b32 s33, s57, s33
	s_or_b32 s57, s33, 0x1000
	v_cmp_ge_u32_e64 s[8:9], v216, s57
	v_cmp_ge_u32_e64 s[12:13], v217, s57
	v_cmp_ge_u32_e64 s[14:15], v218, s57
	v_cmp_ge_u32_e64 s[16:17], v219, s57
	v_cmp_ge_u32_e64 s[18:19], v220, s57
	v_cmp_ge_u32_e64 s[22:23], v221, s57
	s_bcnt1_i32_b64 s89, s[8:9]
	s_bcnt1_i32_b64 s61, s[12:13]
	s_add_u32 s89, s89, s61
	s_bcnt1_i32_b64 s61, s[14:15]
	s_add_u32 s89, s89, s61
	s_bcnt1_i32_b64 s61, s[16:17]
	s_add_u32 s89, s89, s61
	s_bcnt1_i32_b64 s61, s[18:19]
	s_add_u32 s89, s89, s61
	s_bcnt1_i32_b64 s61, s[22:23]
	s_add_u32 s89, s89, s61
	s_cmp_ge_u32 s89, s91
	s_cselect_b32 s33, s57, s33
	s_or_b32 s57, s33, 0x800
	v_cmp_ge_u32_e64 s[8:9], v216, s57
	v_cmp_ge_u32_e64 s[12:13], v217, s57
	v_cmp_ge_u32_e64 s[14:15], v218, s57
	v_cmp_ge_u32_e64 s[16:17], v219, s57
	v_cmp_ge_u32_e64 s[18:19], v220, s57
	v_cmp_ge_u32_e64 s[22:23], v221, s57
	s_bcnt1_i32_b64 s89, s[8:9]
	s_bcnt1_i32_b64 s61, s[12:13]
	s_add_u32 s89, s89, s61
	s_bcnt1_i32_b64 s61, s[14:15]
	s_add_u32 s89, s89, s61
	s_bcnt1_i32_b64 s61, s[16:17]
	s_add_u32 s89, s89, s61
	s_bcnt1_i32_b64 s61, s[18:19]
	s_add_u32 s89, s89, s61
	s_bcnt1_i32_b64 s61, s[22:23]
	s_add_u32 s89, s89, s61
	s_cmp_ge_u32 s89, s91
	s_cselect_b32 s33, s57, s33
	s_or_b32 s57, s33, 0x400
	v_cmp_ge_u32_e64 s[8:9], v216, s57
	v_cmp_ge_u32_e64 s[12:13], v217, s57
	v_cmp_ge_u32_e64 s[14:15], v218, s57
	v_cmp_ge_u32_e64 s[16:17], v219, s57
	v_cmp_ge_u32_e64 s[18:19], v220, s57
	v_cmp_ge_u32_e64 s[22:23], v221, s57
	s_bcnt1_i32_b64 s89, s[8:9]
	s_bcnt1_i32_b64 s61, s[12:13]
	s_add_u32 s89, s89, s61
	s_bcnt1_i32_b64 s61, s[14:15]
	s_add_u32 s89, s89, s61
	s_bcnt1_i32_b64 s61, s[16:17]
	s_add_u32 s89, s89, s61
	s_bcnt1_i32_b64 s61, s[18:19]
	s_add_u32 s89, s89, s61
	s_bcnt1_i32_b64 s61, s[22:23]
	s_add_u32 s89, s89, s61
	s_cmp_ge_u32 s89, s91
	s_cselect_b32 s33, s57, s33
	s_or_b32 s57, s33, 0x200
	v_cmp_ge_u32_e64 s[8:9], v216, s57
	v_cmp_ge_u32_e64 s[12:13], v217, s57
	v_cmp_ge_u32_e64 s[14:15], v218, s57
	v_cmp_ge_u32_e64 s[16:17], v219, s57
	v_cmp_ge_u32_e64 s[18:19], v220, s57
	v_cmp_ge_u32_e64 s[22:23], v221, s57
	s_bcnt1_i32_b64 s89, s[8:9]
	s_bcnt1_i32_b64 s61, s[12:13]
	s_add_u32 s89, s89, s61
	s_bcnt1_i32_b64 s61, s[14:15]
	s_add_u32 s89, s89, s61
	s_bcnt1_i32_b64 s61, s[16:17]
	s_add_u32 s89, s89, s61
	s_bcnt1_i32_b64 s61, s[18:19]
	s_add_u32 s89, s89, s61
	s_bcnt1_i32_b64 s61, s[22:23]
	s_add_u32 s89, s89, s61
	s_cmp_ge_u32 s89, s91
	s_cselect_b32 s33, s57, s33
	s_or_b32 s57, s33, 0x100
	v_cmp_ge_u32_e64 s[8:9], v216, s57
	v_cmp_ge_u32_e64 s[12:13], v217, s57
	v_cmp_ge_u32_e64 s[14:15], v218, s57
	v_cmp_ge_u32_e64 s[16:17], v219, s57
	v_cmp_ge_u32_e64 s[18:19], v220, s57
	v_cmp_ge_u32_e64 s[22:23], v221, s57
	s_bcnt1_i32_b64 s89, s[8:9]
	s_bcnt1_i32_b64 s61, s[12:13]
	s_add_u32 s89, s89, s61
	s_bcnt1_i32_b64 s61, s[14:15]
	s_add_u32 s89, s89, s61
	s_bcnt1_i32_b64 s61, s[16:17]
	s_add_u32 s89, s89, s61
	s_bcnt1_i32_b64 s61, s[18:19]
	s_add_u32 s89, s89, s61
	s_bcnt1_i32_b64 s61, s[22:23]
	s_add_u32 s89, s89, s61
	s_cmp_ge_u32 s89, s91
	s_cselect_b32 s33, s57, s33
	s_or_b32 s57, s33, 0x80
	v_cmp_ge_u32_e64 s[8:9], v216, s57
	v_cmp_ge_u32_e64 s[12:13], v217, s57
	v_cmp_ge_u32_e64 s[14:15], v218, s57
	v_cmp_ge_u32_e64 s[16:17], v219, s57
	v_cmp_ge_u32_e64 s[18:19], v220, s57
	v_cmp_ge_u32_e64 s[22:23], v221, s57
	s_bcnt1_i32_b64 s89, s[8:9]
	s_bcnt1_i32_b64 s61, s[12:13]
	s_add_u32 s89, s89, s61
	s_bcnt1_i32_b64 s61, s[14:15]
	s_add_u32 s89, s89, s61
	s_bcnt1_i32_b64 s61, s[16:17]
	s_add_u32 s89, s89, s61
	s_bcnt1_i32_b64 s61, s[18:19]
	s_add_u32 s89, s89, s61
	s_bcnt1_i32_b64 s61, s[22:23]
	s_add_u32 s89, s89, s61
	s_cmp_ge_u32 s89, s91
	s_cselect_b32 s33, s57, s33
	s_or_b32 s57, s33, 0x40
	v_cmp_ge_u32_e64 s[8:9], v216, s57
	v_cmp_ge_u32_e64 s[12:13], v217, s57
	v_cmp_ge_u32_e64 s[14:15], v218, s57
	v_cmp_ge_u32_e64 s[16:17], v219, s57
	v_cmp_ge_u32_e64 s[18:19], v220, s57
	v_cmp_ge_u32_e64 s[22:23], v221, s57
	s_bcnt1_i32_b64 s89, s[8:9]
	s_bcnt1_i32_b64 s61, s[12:13]
	s_add_u32 s89, s89, s61
	s_bcnt1_i32_b64 s61, s[14:15]
	s_add_u32 s89, s89, s61
	s_bcnt1_i32_b64 s61, s[16:17]
	s_add_u32 s89, s89, s61
	s_bcnt1_i32_b64 s61, s[18:19]
	s_add_u32 s89, s89, s61
	s_bcnt1_i32_b64 s61, s[22:23]
	s_add_u32 s89, s89, s61
	s_cmp_ge_u32 s89, s91
	s_cselect_b32 s33, s57, s33
	s_or_b32 s57, s33, 0x20
	v_cmp_ge_u32_e64 s[8:9], v216, s57
	v_cmp_ge_u32_e64 s[12:13], v217, s57
	v_cmp_ge_u32_e64 s[14:15], v218, s57
	v_cmp_ge_u32_e64 s[16:17], v219, s57
	v_cmp_ge_u32_e64 s[18:19], v220, s57
	v_cmp_ge_u32_e64 s[22:23], v221, s57
	s_bcnt1_i32_b64 s89, s[8:9]
	s_bcnt1_i32_b64 s61, s[12:13]
	s_add_u32 s89, s89, s61
	s_bcnt1_i32_b64 s61, s[14:15]
	s_add_u32 s89, s89, s61
	s_bcnt1_i32_b64 s61, s[16:17]
	s_add_u32 s89, s89, s61
	s_bcnt1_i32_b64 s61, s[18:19]
	s_add_u32 s89, s89, s61
	s_bcnt1_i32_b64 s61, s[22:23]
	s_add_u32 s89, s89, s61
	s_cmp_ge_u32 s89, s91
	s_cselect_b32 s33, s57, s33
	s_or_b32 s57, s33, 0x10
	v_cmp_ge_u32_e64 s[8:9], v216, s57
	v_cmp_ge_u32_e64 s[12:13], v217, s57
	v_cmp_ge_u32_e64 s[14:15], v218, s57
	v_cmp_ge_u32_e64 s[16:17], v219, s57
	v_cmp_ge_u32_e64 s[18:19], v220, s57
	v_cmp_ge_u32_e64 s[22:23], v221, s57
	s_bcnt1_i32_b64 s89, s[8:9]
	s_bcnt1_i32_b64 s61, s[12:13]
	s_add_u32 s89, s89, s61
	s_bcnt1_i32_b64 s61, s[14:15]
	s_add_u32 s89, s89, s61
	s_bcnt1_i32_b64 s61, s[16:17]
	s_add_u32 s89, s89, s61
	s_bcnt1_i32_b64 s61, s[18:19]
	s_add_u32 s89, s89, s61
	s_bcnt1_i32_b64 s61, s[22:23]
	s_add_u32 s89, s89, s61
	s_cmp_ge_u32 s89, s91
	s_cselect_b32 s33, s57, s33
	s_or_b32 s57, s33, 0x8
	v_cmp_ge_u32_e64 s[8:9], v216, s57
	v_cmp_ge_u32_e64 s[12:13], v217, s57
	v_cmp_ge_u32_e64 s[14:15], v218, s57
	v_cmp_ge_u32_e64 s[16:17], v219, s57
	v_cmp_ge_u32_e64 s[18:19], v220, s57
	v_cmp_ge_u32_e64 s[22:23], v221, s57
	s_bcnt1_i32_b64 s89, s[8:9]
	s_bcnt1_i32_b64 s61, s[12:13]
	s_add_u32 s89, s89, s61
	s_bcnt1_i32_b64 s61, s[14:15]
	s_add_u32 s89, s89, s61
	s_bcnt1_i32_b64 s61, s[16:17]
	s_add_u32 s89, s89, s61
	s_bcnt1_i32_b64 s61, s[18:19]
	s_add_u32 s89, s89, s61
	s_bcnt1_i32_b64 s61, s[22:23]
	s_add_u32 s89, s89, s61
	s_cmp_ge_u32 s89, s91
	s_cselect_b32 s33, s57, s33
	s_or_b32 s57, s33, 0x4
	v_cmp_ge_u32_e64 s[8:9], v216, s57
	v_cmp_ge_u32_e64 s[12:13], v217, s57
	v_cmp_ge_u32_e64 s[14:15], v218, s57
	v_cmp_ge_u32_e64 s[16:17], v219, s57
	v_cmp_ge_u32_e64 s[18:19], v220, s57
	v_cmp_ge_u32_e64 s[22:23], v221, s57
	s_bcnt1_i32_b64 s89, s[8:9]
	s_bcnt1_i32_b64 s61, s[12:13]
	s_add_u32 s89, s89, s61
	s_bcnt1_i32_b64 s61, s[14:15]
	s_add_u32 s89, s89, s61
	s_bcnt1_i32_b64 s61, s[16:17]
	s_add_u32 s89, s89, s61
	s_bcnt1_i32_b64 s61, s[18:19]
	s_add_u32 s89, s89, s61
	s_bcnt1_i32_b64 s61, s[22:23]
	s_add_u32 s89, s89, s61
	s_cmp_ge_u32 s89, s91
	s_cselect_b32 s33, s57, s33
	s_or_b32 s57, s33, 0x2
	v_cmp_ge_u32_e64 s[8:9], v216, s57
	v_cmp_ge_u32_e64 s[12:13], v217, s57
	v_cmp_ge_u32_e64 s[14:15], v218, s57
	v_cmp_ge_u32_e64 s[16:17], v219, s57
	v_cmp_ge_u32_e64 s[18:19], v220, s57
	v_cmp_ge_u32_e64 s[22:23], v221, s57
	s_bcnt1_i32_b64 s89, s[8:9]
	s_bcnt1_i32_b64 s61, s[12:13]
	s_add_u32 s89, s89, s61
	s_bcnt1_i32_b64 s61, s[14:15]
	s_add_u32 s89, s89, s61
	s_bcnt1_i32_b64 s61, s[16:17]
	s_add_u32 s89, s89, s61
	s_bcnt1_i32_b64 s61, s[18:19]
	s_add_u32 s89, s89, s61
	s_bcnt1_i32_b64 s61, s[22:23]
	s_add_u32 s89, s89, s61
	s_cmp_ge_u32 s89, s91
	s_cselect_b32 s33, s57, s33
	s_or_b32 s57, s33, 0x1
	v_cmp_ge_u32_e64 s[8:9], v216, s57
	v_cmp_ge_u32_e64 s[12:13], v217, s57
	v_cmp_ge_u32_e64 s[14:15], v218, s57
	v_cmp_ge_u32_e64 s[16:17], v219, s57
	v_cmp_ge_u32_e64 s[18:19], v220, s57
	v_cmp_ge_u32_e64 s[22:23], v221, s57
	s_bcnt1_i32_b64 s89, s[8:9]
	s_bcnt1_i32_b64 s61, s[12:13]
	s_add_u32 s89, s89, s61
	s_bcnt1_i32_b64 s61, s[14:15]
	s_add_u32 s89, s89, s61
	s_bcnt1_i32_b64 s61, s[16:17]
	s_add_u32 s89, s89, s61
	s_bcnt1_i32_b64 s61, s[18:19]
	s_add_u32 s89, s89, s61
	s_bcnt1_i32_b64 s61, s[22:23]
	s_add_u32 s89, s89, s61
	s_cmp_ge_u32 s89, s91
	s_cselect_b32 s33, s57, s33
	v_cmp_gt_u32_e64 s[8:9], v216, s33
	v_cmp_gt_u32_e64 s[12:13], v217, s33
	v_cmp_gt_u32_e64 s[14:15], v218, s33
	v_cmp_gt_u32_e64 s[16:17], v219, s33
	v_cmp_gt_u32_e64 s[18:19], v220, s33
	v_cmp_gt_u32_e64 s[22:23], v221, s33
	s_bcnt1_i32_b64 s89, s[8:9]
	s_bcnt1_i32_b64 s61, s[12:13]
	s_add_u32 s89, s89, s61
	s_bcnt1_i32_b64 s61, s[14:15]
	s_add_u32 s89, s89, s61
	s_bcnt1_i32_b64 s61, s[16:17]
	s_add_u32 s89, s89, s61
	s_bcnt1_i32_b64 s61, s[18:19]
	s_add_u32 s89, s89, s61
	s_bcnt1_i32_b64 s61, s[22:23]
	s_add_u32 s89, s89, s61
	s_sub_u32 s91, s91, s89
	v_cmp_eq_u32_e64 s[8:9], v216, s33
	v_cmp_eq_u32_e64 s[12:13], v217, s33
	v_cmp_eq_u32_e64 s[14:15], v218, s33
	v_cmp_eq_u32_e64 s[16:17], v219, s33
	v_cmp_eq_u32_e64 s[18:19], v220, s33
	v_cmp_eq_u32_e64 s[22:23], v221, s33
	s_bcnt1_i32_b64 s89, s[8:9]
	s_bcnt1_i32_b64 s61, s[12:13]
	s_add_u32 s89, s89, s61
	s_bcnt1_i32_b64 s61, s[14:15]
	s_add_u32 s89, s89, s61
	s_bcnt1_i32_b64 s61, s[16:17]
	s_add_u32 s89, s89, s61
	s_bcnt1_i32_b64 s61, s[18:19]
	s_add_u32 s89, s89, s61
	s_bcnt1_i32_b64 s61, s[22:23]
	s_add_u32 s89, s89, s61
	s_add_u32 s57, s33, 1
	s_cmp_eq_u32 s91, s89
	s_cselect_b32 s57, s33, s57
	s_cselect_b32 s60, 1, 0
	v_cmp_ge_u32_e64 s[8:9], v216, s57
	v_cmp_ge_u32_e64 s[12:13], v217, s57
	v_cmp_ge_u32_e64 s[14:15], v218, s57
	v_cmp_ge_u32_e64 s[16:17], v219, s57
	v_cmp_ge_u32_e64 s[18:19], v220, s57
	v_cmp_ge_u32_e64 s[22:23], v221, s57
	s_nop 1
	v_mbcnt_lo_u32_b32 v241, s8, 0
	v_mbcnt_hi_u32_b32 v241, s9, v241
	v_add_u32_e32 v241, s90, v241
	v_and_b32_e32 v241, 0xff, v241
	v_lshl_add_u32 v241, v241, 1, v246
	s_mov_b64 exec, s[8:9]
	ds_write_b16 v241, v224
	s_mov_b64 exec, -1
	s_bcnt1_i32_b64 s61, s[8:9]
	s_add_u32 s90, s90, s61
	v_mbcnt_lo_u32_b32 v241, s12, 0
	v_mbcnt_hi_u32_b32 v241, s13, v241
	v_add_u32_e32 v241, s90, v241
	v_and_b32_e32 v241, 0xff, v241
	v_lshl_add_u32 v241, v241, 1, v246
	s_mov_b64 exec, s[12:13]
	ds_write_b16 v241, v225
	s_mov_b64 exec, -1
	s_bcnt1_i32_b64 s61, s[12:13]
	s_add_u32 s90, s90, s61
	v_mbcnt_lo_u32_b32 v241, s14, 0
	v_mbcnt_hi_u32_b32 v241, s15, v241
	v_add_u32_e32 v241, s90, v241
	v_and_b32_e32 v241, 0xff, v241
	v_lshl_add_u32 v241, v241, 1, v246
	s_mov_b64 exec, s[14:15]
	ds_write_b16 v241, v226
	s_mov_b64 exec, -1
	s_bcnt1_i32_b64 s61, s[14:15]
	s_add_u32 s90, s90, s61
	v_mbcnt_lo_u32_b32 v241, s16, 0
	v_mbcnt_hi_u32_b32 v241, s17, v241
	v_add_u32_e32 v241, s90, v241
	v_and_b32_e32 v241, 0xff, v241
	v_lshl_add_u32 v241, v241, 1, v246
	s_mov_b64 exec, s[16:17]
	ds_write_b16 v241, v227
	s_mov_b64 exec, -1
	s_bcnt1_i32_b64 s61, s[16:17]
	s_add_u32 s90, s90, s61
	v_mbcnt_lo_u32_b32 v241, s18, 0
	v_mbcnt_hi_u32_b32 v241, s19, v241
	v_add_u32_e32 v241, s90, v241
	v_and_b32_e32 v241, 0xff, v241
	v_lshl_add_u32 v241, v241, 1, v246
	s_mov_b64 exec, s[18:19]
	ds_write_b16 v241, v228
	s_mov_b64 exec, -1
	s_bcnt1_i32_b64 s61, s[18:19]
	s_add_u32 s90, s90, s61
	v_mbcnt_lo_u32_b32 v241, s22, 0
	v_mbcnt_hi_u32_b32 v241, s23, v241
	v_add_u32_e32 v241, s90, v241
	v_and_b32_e32 v241, 0xff, v241
	v_lshl_add_u32 v241, v241, 1, v246
	s_mov_b64 exec, s[22:23]
	ds_write_b16 v241, v229
	s_mov_b64 exec, -1
	s_bcnt1_i32_b64 s61, s[22:23]
	s_add_u32 s90, s90, s61
	s_mov_b32 s92, 0
	s_cmp_lg_u32 s60, 0
	s_cbranch_scc1 .Lref_fin
	v_cmp_eq_u32_e64 s[8:9], v216, s33
	v_cmp_eq_u32_e64 s[12:13], v217, s33
	v_cmp_eq_u32_e64 s[14:15], v218, s33
	v_cmp_eq_u32_e64 s[16:17], v219, s33
	v_cmp_eq_u32_e64 s[18:19], v220, s33
	v_cmp_eq_u32_e64 s[22:23], v221, s33
	s_nop 1
	v_mbcnt_lo_u32_b32 v241, s8, 0
	v_mbcnt_hi_u32_b32 v241, s9, v241
	v_add_u32_e32 v241, s92, v241
	v_lshl_add_u32 v241, v241, 1, v244
	s_mov_b64 exec, s[8:9]
	ds_write_b16 v241, v224
	s_mov_b64 exec, -1
	s_bcnt1_i32_b64 s61, s[8:9]
	s_add_u32 s92, s92, s61
	v_mbcnt_lo_u32_b32 v241, s12, 0
	v_mbcnt_hi_u32_b32 v241, s13, v241
	v_add_u32_e32 v241, s92, v241
	v_lshl_add_u32 v241, v241, 1, v244
	s_mov_b64 exec, s[12:13]
	ds_write_b16 v241, v225
	s_mov_b64 exec, -1
	s_bcnt1_i32_b64 s61, s[12:13]
	s_add_u32 s92, s92, s61
	v_mbcnt_lo_u32_b32 v241, s14, 0
	v_mbcnt_hi_u32_b32 v241, s15, v241
	v_add_u32_e32 v241, s92, v241
	v_lshl_add_u32 v241, v241, 1, v244
	s_mov_b64 exec, s[14:15]
	ds_write_b16 v241, v226
	s_mov_b64 exec, -1
	s_bcnt1_i32_b64 s61, s[14:15]
	s_add_u32 s92, s92, s61
	v_mbcnt_lo_u32_b32 v241, s16, 0
	v_mbcnt_hi_u32_b32 v241, s17, v241
	v_add_u32_e32 v241, s92, v241
	v_lshl_add_u32 v241, v241, 1, v244
	s_mov_b64 exec, s[16:17]
	ds_write_b16 v241, v227
	s_mov_b64 exec, -1
	s_bcnt1_i32_b64 s61, s[16:17]
	s_add_u32 s92, s92, s61
	v_mbcnt_lo_u32_b32 v241, s18, 0
	v_mbcnt_hi_u32_b32 v241, s19, v241
	v_add_u32_e32 v241, s92, v241
	v_lshl_add_u32 v241, v241, 1, v244
	s_mov_b64 exec, s[18:19]
	ds_write_b16 v241, v228
	s_mov_b64 exec, -1
	s_bcnt1_i32_b64 s61, s[18:19]
	s_add_u32 s92, s92, s61
	v_mbcnt_lo_u32_b32 v241, s22, 0
	v_mbcnt_hi_u32_b32 v241, s23, v241
	v_add_u32_e32 v241, s92, v241
	v_lshl_add_u32 v241, v241, 1, v244
	s_mov_b64 exec, s[22:23]
	ds_write_b16 v241, v229
	s_mov_b64 exec, -1
	s_bcnt1_i32_b64 s61, s[22:23]
	s_add_u32 s92, s92, s61
	s_branch .Lref_fin
.Lref_v5:
	ds_read_b32 v216, v238
	ds_read_u16 v224, v245
	ds_read_b32 v217, v238 offset:256
	ds_read_u16 v225, v245 offset:128
	ds_read_b32 v218, v238 offset:512
	ds_read_u16 v226, v245 offset:256
	ds_read_b32 v219, v238 offset:768
	ds_read_u16 v227, v245 offset:384
	ds_read_b32 v220, v238 offset:1024
	ds_read_u16 v228, v245 offset:512
	v_cmp_gt_u32_e64 s[8:9], s93, v145
	v_add_u32_e32 v241, 64, v145
	v_cmp_gt_u32_e64 s[12:13], s93, v241
	v_add_u32_e32 v241, 128, v145
	v_cmp_gt_u32_e64 s[14:15], s93, v241
	v_add_u32_e32 v241, 192, v145
	v_cmp_gt_u32_e64 s[16:17], s93, v241
	v_add_u32_e32 v241, 256, v145
	v_cmp_gt_u32_e64 s[18:19], s93, v241
	s_waitcnt lgkmcnt(0)
	v_cndmask_b32_e64 v216, 0, v216, s[8:9]
	v_cndmask_b32_e64 v217, 0, v217, s[12:13]
	v_cndmask_b32_e64 v218, 0, v218, s[14:15]
	v_cndmask_b32_e64 v219, 0, v219, s[16:17]
	v_cndmask_b32_e64 v220, 0, v220, s[18:19]
	s_or_b32 s57, s33, 0x100000
	v_cmp_ge_u32_e64 s[8:9], v216, s57
	v_cmp_ge_u32_e64 s[12:13], v217, s57
	v_cmp_ge_u32_e64 s[14:15], v218, s57
	v_cmp_ge_u32_e64 s[16:17], v219, s57
	v_cmp_ge_u32_e64 s[18:19], v220, s57
	s_bcnt1_i32_b64 s89, s[8:9]
	s_bcnt1_i32_b64 s61, s[12:13]
	s_add_u32 s89, s89, s61
	s_bcnt1_i32_b64 s61, s[14:15]
	s_add_u32 s89, s89, s61
	s_bcnt1_i32_b64 s61, s[16:17]
	s_add_u32 s89, s89, s61
	s_bcnt1_i32_b64 s61, s[18:19]
	s_add_u32 s89, s89, s61
	s_cmp_ge_u32 s89, s91
	s_cselect_b32 s33, s57, s33
	s_or_b32 s57, s33, 0x80000
	v_cmp_ge_u32_e64 s[8:9], v216, s57
	v_cmp_ge_u32_e64 s[12:13], v217, s57
	v_cmp_ge_u32_e64 s[14:15], v218, s57
	v_cmp_ge_u32_e64 s[16:17], v219, s57
	v_cmp_ge_u32_e64 s[18:19], v220, s57
	s_bcnt1_i32_b64 s89, s[8:9]
	s_bcnt1_i32_b64 s61, s[12:13]
	s_add_u32 s89, s89, s61
	s_bcnt1_i32_b64 s61, s[14:15]
	s_add_u32 s89, s89, s61
	s_bcnt1_i32_b64 s61, s[16:17]
	s_add_u32 s89, s89, s61
	s_bcnt1_i32_b64 s61, s[18:19]
	s_add_u32 s89, s89, s61
	s_cmp_ge_u32 s89, s91
	s_cselect_b32 s33, s57, s33
	s_or_b32 s57, s33, 0x40000
	v_cmp_ge_u32_e64 s[8:9], v216, s57
	v_cmp_ge_u32_e64 s[12:13], v217, s57
	v_cmp_ge_u32_e64 s[14:15], v218, s57
	v_cmp_ge_u32_e64 s[16:17], v219, s57
	v_cmp_ge_u32_e64 s[18:19], v220, s57
	s_bcnt1_i32_b64 s89, s[8:9]
	s_bcnt1_i32_b64 s61, s[12:13]
	s_add_u32 s89, s89, s61
	s_bcnt1_i32_b64 s61, s[14:15]
	s_add_u32 s89, s89, s61
	s_bcnt1_i32_b64 s61, s[16:17]
	s_add_u32 s89, s89, s61
	s_bcnt1_i32_b64 s61, s[18:19]
	s_add_u32 s89, s89, s61
	s_cmp_ge_u32 s89, s91
	s_cselect_b32 s33, s57, s33
	s_or_b32 s57, s33, 0x20000
	v_cmp_ge_u32_e64 s[8:9], v216, s57
	v_cmp_ge_u32_e64 s[12:13], v217, s57
	v_cmp_ge_u32_e64 s[14:15], v218, s57
	v_cmp_ge_u32_e64 s[16:17], v219, s57
	v_cmp_ge_u32_e64 s[18:19], v220, s57
	s_bcnt1_i32_b64 s89, s[8:9]
	s_bcnt1_i32_b64 s61, s[12:13]
	s_add_u32 s89, s89, s61
	s_bcnt1_i32_b64 s61, s[14:15]
	s_add_u32 s89, s89, s61
	s_bcnt1_i32_b64 s61, s[16:17]
	s_add_u32 s89, s89, s61
	s_bcnt1_i32_b64 s61, s[18:19]
	s_add_u32 s89, s89, s61
	s_cmp_ge_u32 s89, s91
	s_cselect_b32 s33, s57, s33
	s_or_b32 s57, s33, 0x10000
	v_cmp_ge_u32_e64 s[8:9], v216, s57
	v_cmp_ge_u32_e64 s[12:13], v217, s57
	v_cmp_ge_u32_e64 s[14:15], v218, s57
	v_cmp_ge_u32_e64 s[16:17], v219, s57
	v_cmp_ge_u32_e64 s[18:19], v220, s57
	s_bcnt1_i32_b64 s89, s[8:9]
	s_bcnt1_i32_b64 s61, s[12:13]
	s_add_u32 s89, s89, s61
	s_bcnt1_i32_b64 s61, s[14:15]
	s_add_u32 s89, s89, s61
	s_bcnt1_i32_b64 s61, s[16:17]
	s_add_u32 s89, s89, s61
	s_bcnt1_i32_b64 s61, s[18:19]
	s_add_u32 s89, s89, s61
	s_cmp_ge_u32 s89, s91
	s_cselect_b32 s33, s57, s33
	s_or_b32 s57, s33, 0x8000
	v_cmp_ge_u32_e64 s[8:9], v216, s57
	v_cmp_ge_u32_e64 s[12:13], v217, s57
	v_cmp_ge_u32_e64 s[14:15], v218, s57
	v_cmp_ge_u32_e64 s[16:17], v219, s57
	v_cmp_ge_u32_e64 s[18:19], v220, s57
	s_bcnt1_i32_b64 s89, s[8:9]
	s_bcnt1_i32_b64 s61, s[12:13]
	s_add_u32 s89, s89, s61
	s_bcnt1_i32_b64 s61, s[14:15]
	s_add_u32 s89, s89, s61
	s_bcnt1_i32_b64 s61, s[16:17]
	s_add_u32 s89, s89, s61
	s_bcnt1_i32_b64 s61, s[18:19]
	s_add_u32 s89, s89, s61
	s_cmp_ge_u32 s89, s91
	s_cselect_b32 s33, s57, s33
	s_or_b32 s57, s33, 0x4000
	v_cmp_ge_u32_e64 s[8:9], v216, s57
	v_cmp_ge_u32_e64 s[12:13], v217, s57
	v_cmp_ge_u32_e64 s[14:15], v218, s57
	v_cmp_ge_u32_e64 s[16:17], v219, s57
	v_cmp_ge_u32_e64 s[18:19], v220, s57
	s_bcnt1_i32_b64 s89, s[8:9]
	s_bcnt1_i32_b64 s61, s[12:13]
	s_add_u32 s89, s89, s61
	s_bcnt1_i32_b64 s61, s[14:15]
	s_add_u32 s89, s89, s61
	s_bcnt1_i32_b64 s61, s[16:17]
	s_add_u32 s89, s89, s61
	s_bcnt1_i32_b64 s61, s[18:19]
	s_add_u32 s89, s89, s61
	s_cmp_ge_u32 s89, s91
	s_cselect_b32 s33, s57, s33
	s_or_b32 s57, s33, 0x2000
	v_cmp_ge_u32_e64 s[8:9], v216, s57
	v_cmp_ge_u32_e64 s[12:13], v217, s57
	v_cmp_ge_u32_e64 s[14:15], v218, s57
	v_cmp_ge_u32_e64 s[16:17], v219, s57
	v_cmp_ge_u32_e64 s[18:19], v220, s57
	s_bcnt1_i32_b64 s89, s[8:9]
	s_bcnt1_i32_b64 s61, s[12:13]
	s_add_u32 s89, s89, s61
	s_bcnt1_i32_b64 s61, s[14:15]
	s_add_u32 s89, s89, s61
	s_bcnt1_i32_b64 s61, s[16:17]
	s_add_u32 s89, s89, s61
	s_bcnt1_i32_b64 s61, s[18:19]
	s_add_u32 s89, s89, s61
	s_cmp_ge_u32 s89, s91
	s_cselect_b32 s33, s57, s33
	s_or_b32 s57, s33, 0x1000
	v_cmp_ge_u32_e64 s[8:9], v216, s57
	v_cmp_ge_u32_e64 s[12:13], v217, s57
	v_cmp_ge_u32_e64 s[14:15], v218, s57
	v_cmp_ge_u32_e64 s[16:17], v219, s57
	v_cmp_ge_u32_e64 s[18:19], v220, s57
	s_bcnt1_i32_b64 s89, s[8:9]
	s_bcnt1_i32_b64 s61, s[12:13]
	s_add_u32 s89, s89, s61
	s_bcnt1_i32_b64 s61, s[14:15]
	s_add_u32 s89, s89, s61
	s_bcnt1_i32_b64 s61, s[16:17]
	s_add_u32 s89, s89, s61
	s_bcnt1_i32_b64 s61, s[18:19]
	s_add_u32 s89, s89, s61
	s_cmp_ge_u32 s89, s91
	s_cselect_b32 s33, s57, s33
	s_or_b32 s57, s33, 0x800
	v_cmp_ge_u32_e64 s[8:9], v216, s57
	v_cmp_ge_u32_e64 s[12:13], v217, s57
	v_cmp_ge_u32_e64 s[14:15], v218, s57
	v_cmp_ge_u32_e64 s[16:17], v219, s57
	v_cmp_ge_u32_e64 s[18:19], v220, s57
	s_bcnt1_i32_b64 s89, s[8:9]
	s_bcnt1_i32_b64 s61, s[12:13]
	s_add_u32 s89, s89, s61
	s_bcnt1_i32_b64 s61, s[14:15]
	s_add_u32 s89, s89, s61
	s_bcnt1_i32_b64 s61, s[16:17]
	s_add_u32 s89, s89, s61
	s_bcnt1_i32_b64 s61, s[18:19]
	s_add_u32 s89, s89, s61
	s_cmp_ge_u32 s89, s91
	s_cselect_b32 s33, s57, s33
	s_or_b32 s57, s33, 0x400
	v_cmp_ge_u32_e64 s[8:9], v216, s57
	v_cmp_ge_u32_e64 s[12:13], v217, s57
	v_cmp_ge_u32_e64 s[14:15], v218, s57
	v_cmp_ge_u32_e64 s[16:17], v219, s57
	v_cmp_ge_u32_e64 s[18:19], v220, s57
	s_bcnt1_i32_b64 s89, s[8:9]
	s_bcnt1_i32_b64 s61, s[12:13]
	s_add_u32 s89, s89, s61
	s_bcnt1_i32_b64 s61, s[14:15]
	s_add_u32 s89, s89, s61
	s_bcnt1_i32_b64 s61, s[16:17]
	s_add_u32 s89, s89, s61
	s_bcnt1_i32_b64 s61, s[18:19]
	s_add_u32 s89, s89, s61
	s_cmp_ge_u32 s89, s91
	s_cselect_b32 s33, s57, s33
	s_or_b32 s57, s33, 0x200
	v_cmp_ge_u32_e64 s[8:9], v216, s57
	v_cmp_ge_u32_e64 s[12:13], v217, s57
	v_cmp_ge_u32_e64 s[14:15], v218, s57
	v_cmp_ge_u32_e64 s[16:17], v219, s57
	v_cmp_ge_u32_e64 s[18:19], v220, s57
	s_bcnt1_i32_b64 s89, s[8:9]
	s_bcnt1_i32_b64 s61, s[12:13]
	s_add_u32 s89, s89, s61
	s_bcnt1_i32_b64 s61, s[14:15]
	s_add_u32 s89, s89, s61
	s_bcnt1_i32_b64 s61, s[16:17]
	s_add_u32 s89, s89, s61
	s_bcnt1_i32_b64 s61, s[18:19]
	s_add_u32 s89, s89, s61
	s_cmp_ge_u32 s89, s91
	s_cselect_b32 s33, s57, s33
	s_or_b32 s57, s33, 0x100
	v_cmp_ge_u32_e64 s[8:9], v216, s57
	v_cmp_ge_u32_e64 s[12:13], v217, s57
	v_cmp_ge_u32_e64 s[14:15], v218, s57
	v_cmp_ge_u32_e64 s[16:17], v219, s57
	v_cmp_ge_u32_e64 s[18:19], v220, s57
	s_bcnt1_i32_b64 s89, s[8:9]
	s_bcnt1_i32_b64 s61, s[12:13]
	s_add_u32 s89, s89, s61
	s_bcnt1_i32_b64 s61, s[14:15]
	s_add_u32 s89, s89, s61
	s_bcnt1_i32_b64 s61, s[16:17]
	s_add_u32 s89, s89, s61
	s_bcnt1_i32_b64 s61, s[18:19]
	s_add_u32 s89, s89, s61
	s_cmp_ge_u32 s89, s91
	s_cselect_b32 s33, s57, s33
	s_or_b32 s57, s33, 0x80
	v_cmp_ge_u32_e64 s[8:9], v216, s57
	v_cmp_ge_u32_e64 s[12:13], v217, s57
	v_cmp_ge_u32_e64 s[14:15], v218, s57
	v_cmp_ge_u32_e64 s[16:17], v219, s57
	v_cmp_ge_u32_e64 s[18:19], v220, s57
	s_bcnt1_i32_b64 s89, s[8:9]
	s_bcnt1_i32_b64 s61, s[12:13]
	s_add_u32 s89, s89, s61
	s_bcnt1_i32_b64 s61, s[14:15]
	s_add_u32 s89, s89, s61
	s_bcnt1_i32_b64 s61, s[16:17]
	s_add_u32 s89, s89, s61
	s_bcnt1_i32_b64 s61, s[18:19]
	s_add_u32 s89, s89, s61
	s_cmp_ge_u32 s89, s91
	s_cselect_b32 s33, s57, s33
	s_or_b32 s57, s33, 0x40
	v_cmp_ge_u32_e64 s[8:9], v216, s57
	v_cmp_ge_u32_e64 s[12:13], v217, s57
	v_cmp_ge_u32_e64 s[14:15], v218, s57
	v_cmp_ge_u32_e64 s[16:17], v219, s57
	v_cmp_ge_u32_e64 s[18:19], v220, s57
	s_bcnt1_i32_b64 s89, s[8:9]
	s_bcnt1_i32_b64 s61, s[12:13]
	s_add_u32 s89, s89, s61
	s_bcnt1_i32_b64 s61, s[14:15]
	s_add_u32 s89, s89, s61
	s_bcnt1_i32_b64 s61, s[16:17]
	s_add_u32 s89, s89, s61
	s_bcnt1_i32_b64 s61, s[18:19]
	s_add_u32 s89, s89, s61
	s_cmp_ge_u32 s89, s91
	s_cselect_b32 s33, s57, s33
	s_or_b32 s57, s33, 0x20
	v_cmp_ge_u32_e64 s[8:9], v216, s57
	v_cmp_ge_u32_e64 s[12:13], v217, s57
	v_cmp_ge_u32_e64 s[14:15], v218, s57
	v_cmp_ge_u32_e64 s[16:17], v219, s57
	v_cmp_ge_u32_e64 s[18:19], v220, s57
	s_bcnt1_i32_b64 s89, s[8:9]
	s_bcnt1_i32_b64 s61, s[12:13]
	s_add_u32 s89, s89, s61
	s_bcnt1_i32_b64 s61, s[14:15]
	s_add_u32 s89, s89, s61
	s_bcnt1_i32_b64 s61, s[16:17]
	s_add_u32 s89, s89, s61
	s_bcnt1_i32_b64 s61, s[18:19]
	s_add_u32 s89, s89, s61
	s_cmp_ge_u32 s89, s91
	s_cselect_b32 s33, s57, s33
	s_or_b32 s57, s33, 0x10
	v_cmp_ge_u32_e64 s[8:9], v216, s57
	v_cmp_ge_u32_e64 s[12:13], v217, s57
	v_cmp_ge_u32_e64 s[14:15], v218, s57
	v_cmp_ge_u32_e64 s[16:17], v219, s57
	v_cmp_ge_u32_e64 s[18:19], v220, s57
	s_bcnt1_i32_b64 s89, s[8:9]
	s_bcnt1_i32_b64 s61, s[12:13]
	s_add_u32 s89, s89, s61
	s_bcnt1_i32_b64 s61, s[14:15]
	s_add_u32 s89, s89, s61
	s_bcnt1_i32_b64 s61, s[16:17]
	s_add_u32 s89, s89, s61
	s_bcnt1_i32_b64 s61, s[18:19]
	s_add_u32 s89, s89, s61
	s_cmp_ge_u32 s89, s91
	s_cselect_b32 s33, s57, s33
	s_or_b32 s57, s33, 0x8
	v_cmp_ge_u32_e64 s[8:9], v216, s57
	v_cmp_ge_u32_e64 s[12:13], v217, s57
	v_cmp_ge_u32_e64 s[14:15], v218, s57
	v_cmp_ge_u32_e64 s[16:17], v219, s57
	v_cmp_ge_u32_e64 s[18:19], v220, s57
	s_bcnt1_i32_b64 s89, s[8:9]
	s_bcnt1_i32_b64 s61, s[12:13]
	s_add_u32 s89, s89, s61
	s_bcnt1_i32_b64 s61, s[14:15]
	s_add_u32 s89, s89, s61
	s_bcnt1_i32_b64 s61, s[16:17]
	s_add_u32 s89, s89, s61
	s_bcnt1_i32_b64 s61, s[18:19]
	s_add_u32 s89, s89, s61
	s_cmp_ge_u32 s89, s91
	s_cselect_b32 s33, s57, s33
	s_or_b32 s57, s33, 0x4
	v_cmp_ge_u32_e64 s[8:9], v216, s57
	v_cmp_ge_u32_e64 s[12:13], v217, s57
	v_cmp_ge_u32_e64 s[14:15], v218, s57
	v_cmp_ge_u32_e64 s[16:17], v219, s57
	v_cmp_ge_u32_e64 s[18:19], v220, s57
	s_bcnt1_i32_b64 s89, s[8:9]
	s_bcnt1_i32_b64 s61, s[12:13]
	s_add_u32 s89, s89, s61
	s_bcnt1_i32_b64 s61, s[14:15]
	s_add_u32 s89, s89, s61
	s_bcnt1_i32_b64 s61, s[16:17]
	s_add_u32 s89, s89, s61
	s_bcnt1_i32_b64 s61, s[18:19]
	s_add_u32 s89, s89, s61
	s_cmp_ge_u32 s89, s91
	s_cselect_b32 s33, s57, s33
	s_or_b32 s57, s33, 0x2
	v_cmp_ge_u32_e64 s[8:9], v216, s57
	v_cmp_ge_u32_e64 s[12:13], v217, s57
	v_cmp_ge_u32_e64 s[14:15], v218, s57
	v_cmp_ge_u32_e64 s[16:17], v219, s57
	v_cmp_ge_u32_e64 s[18:19], v220, s57
	s_bcnt1_i32_b64 s89, s[8:9]
	s_bcnt1_i32_b64 s61, s[12:13]
	s_add_u32 s89, s89, s61
	s_bcnt1_i32_b64 s61, s[14:15]
	s_add_u32 s89, s89, s61
	s_bcnt1_i32_b64 s61, s[16:17]
	s_add_u32 s89, s89, s61
	s_bcnt1_i32_b64 s61, s[18:19]
	s_add_u32 s89, s89, s61
	s_cmp_ge_u32 s89, s91
	s_cselect_b32 s33, s57, s33
	s_or_b32 s57, s33, 0x1
	v_cmp_ge_u32_e64 s[8:9], v216, s57
	v_cmp_ge_u32_e64 s[12:13], v217, s57
	v_cmp_ge_u32_e64 s[14:15], v218, s57
	v_cmp_ge_u32_e64 s[16:17], v219, s57
	v_cmp_ge_u32_e64 s[18:19], v220, s57
	s_bcnt1_i32_b64 s89, s[8:9]
	s_bcnt1_i32_b64 s61, s[12:13]
	s_add_u32 s89, s89, s61
	s_bcnt1_i32_b64 s61, s[14:15]
	s_add_u32 s89, s89, s61
	s_bcnt1_i32_b64 s61, s[16:17]
	s_add_u32 s89, s89, s61
	s_bcnt1_i32_b64 s61, s[18:19]
	s_add_u32 s89, s89, s61
	s_cmp_ge_u32 s89, s91
	s_cselect_b32 s33, s57, s33
	v_cmp_gt_u32_e64 s[8:9], v216, s33
	v_cmp_gt_u32_e64 s[12:13], v217, s33
	v_cmp_gt_u32_e64 s[14:15], v218, s33
	v_cmp_gt_u32_e64 s[16:17], v219, s33
	v_cmp_gt_u32_e64 s[18:19], v220, s33
	s_bcnt1_i32_b64 s89, s[8:9]
	s_bcnt1_i32_b64 s61, s[12:13]
	s_add_u32 s89, s89, s61
	s_bcnt1_i32_b64 s61, s[14:15]
	s_add_u32 s89, s89, s61
	s_bcnt1_i32_b64 s61, s[16:17]
	s_add_u32 s89, s89, s61
	s_bcnt1_i32_b64 s61, s[18:19]
	s_add_u32 s89, s89, s61
	s_sub_u32 s91, s91, s89
	v_cmp_eq_u32_e64 s[8:9], v216, s33
	v_cmp_eq_u32_e64 s[12:13], v217, s33
	v_cmp_eq_u32_e64 s[14:15], v218, s33
	v_cmp_eq_u32_e64 s[16:17], v219, s33
	v_cmp_eq_u32_e64 s[18:19], v220, s33
	s_bcnt1_i32_b64 s89, s[8:9]
	s_bcnt1_i32_b64 s61, s[12:13]
	s_add_u32 s89, s89, s61
	s_bcnt1_i32_b64 s61, s[14:15]
	s_add_u32 s89, s89, s61
	s_bcnt1_i32_b64 s61, s[16:17]
	s_add_u32 s89, s89, s61
	s_bcnt1_i32_b64 s61, s[18:19]
	s_add_u32 s89, s89, s61
	s_add_u32 s57, s33, 1
	s_cmp_eq_u32 s91, s89
	s_cselect_b32 s57, s33, s57
	s_cselect_b32 s60, 1, 0
	v_cmp_ge_u32_e64 s[8:9], v216, s57
	v_cmp_ge_u32_e64 s[12:13], v217, s57
	v_cmp_ge_u32_e64 s[14:15], v218, s57
	v_cmp_ge_u32_e64 s[16:17], v219, s57
	v_cmp_ge_u32_e64 s[18:19], v220, s57
	s_nop 1
	v_mbcnt_lo_u32_b32 v241, s8, 0
	v_mbcnt_hi_u32_b32 v241, s9, v241
	v_add_u32_e32 v241, s90, v241
	v_and_b32_e32 v241, 0xff, v241
	v_lshl_add_u32 v241, v241, 1, v246
	s_mov_b64 exec, s[8:9]
	ds_write_b16 v241, v224
	s_mov_b64 exec, -1
	s_bcnt1_i32_b64 s61, s[8:9]
	s_add_u32 s90, s90, s61
	v_mbcnt_lo_u32_b32 v241, s12, 0
	v_mbcnt_hi_u32_b32 v241, s13, v241
	v_add_u32_e32 v241, s90, v241
	v_and_b32_e32 v241, 0xff, v241
	v_lshl_add_u32 v241, v241, 1, v246
	s_mov_b64 exec, s[12:13]
	ds_write_b16 v241, v225
	s_mov_b64 exec, -1
	s_bcnt1_i32_b64 s61, s[12:13]
	s_add_u32 s90, s90, s61
	v_mbcnt_lo_u32_b32 v241, s14, 0
	v_mbcnt_hi_u32_b32 v241, s15, v241
	v_add_u32_e32 v241, s90, v241
	v_and_b32_e32 v241, 0xff, v241
	v_lshl_add_u32 v241, v241, 1, v246
	s_mov_b64 exec, s[14:15]
	ds_write_b16 v241, v226
	s_mov_b64 exec, -1
	s_bcnt1_i32_b64 s61, s[14:15]
	s_add_u32 s90, s90, s61
	v_mbcnt_lo_u32_b32 v241, s16, 0
	v_mbcnt_hi_u32_b32 v241, s17, v241
	v_add_u32_e32 v241, s90, v241
	v_and_b32_e32 v241, 0xff, v241
	v_lshl_add_u32 v241, v241, 1, v246
	s_mov_b64 exec, s[16:17]
	ds_write_b16 v241, v227
	s_mov_b64 exec, -1
	s_bcnt1_i32_b64 s61, s[16:17]
	s_add_u32 s90, s90, s61
	v_mbcnt_lo_u32_b32 v241, s18, 0
	v_mbcnt_hi_u32_b32 v241, s19, v241
	v_add_u32_e32 v241, s90, v241
	v_and_b32_e32 v241, 0xff, v241
	v_lshl_add_u32 v241, v241, 1, v246
	s_mov_b64 exec, s[18:19]
	ds_write_b16 v241, v228
	s_mov_b64 exec, -1
	s_bcnt1_i32_b64 s61, s[18:19]
	s_add_u32 s90, s90, s61
	s_mov_b32 s92, 0
	s_cmp_lg_u32 s60, 0
	s_cbranch_scc1 .Lref_fin
	v_cmp_eq_u32_e64 s[8:9], v216, s33
	v_cmp_eq_u32_e64 s[12:13], v217, s33
	v_cmp_eq_u32_e64 s[14:15], v218, s33
	v_cmp_eq_u32_e64 s[16:17], v219, s33
	v_cmp_eq_u32_e64 s[18:19], v220, s33
	s_nop 1
	v_mbcnt_lo_u32_b32 v241, s8, 0
	v_mbcnt_hi_u32_b32 v241, s9, v241
	v_add_u32_e32 v241, s92, v241
	v_lshl_add_u32 v241, v241, 1, v244
	s_mov_b64 exec, s[8:9]
	ds_write_b16 v241, v224
	s_mov_b64 exec, -1
	s_bcnt1_i32_b64 s61, s[8:9]
	s_add_u32 s92, s92, s61
	v_mbcnt_lo_u32_b32 v241, s12, 0
	v_mbcnt_hi_u32_b32 v241, s13, v241
	v_add_u32_e32 v241, s92, v241
	v_lshl_add_u32 v241, v241, 1, v244
	s_mov_b64 exec, s[12:13]
	ds_write_b16 v241, v225
	s_mov_b64 exec, -1
	s_bcnt1_i32_b64 s61, s[12:13]
	s_add_u32 s92, s92, s61
	v_mbcnt_lo_u32_b32 v241, s14, 0
	v_mbcnt_hi_u32_b32 v241, s15, v241
	v_add_u32_e32 v241, s92, v241
	v_lshl_add_u32 v241, v241, 1, v244
	s_mov_b64 exec, s[14:15]
	ds_write_b16 v241, v226
	s_mov_b64 exec, -1
	s_bcnt1_i32_b64 s61, s[14:15]
	s_add_u32 s92, s92, s61
	v_mbcnt_lo_u32_b32 v241, s16, 0
	v_mbcnt_hi_u32_b32 v241, s17, v241
	v_add_u32_e32 v241, s92, v241
	v_lshl_add_u32 v241, v241, 1, v244
	s_mov_b64 exec, s[16:17]
	ds_write_b16 v241, v227
	s_mov_b64 exec, -1
	s_bcnt1_i32_b64 s61, s[16:17]
	s_add_u32 s92, s92, s61
	v_mbcnt_lo_u32_b32 v241, s18, 0
	v_mbcnt_hi_u32_b32 v241, s19, v241
	v_add_u32_e32 v241, s92, v241
	v_lshl_add_u32 v241, v241, 1, v244
	s_mov_b64 exec, s[18:19]
	ds_write_b16 v241, v228
	s_mov_b64 exec, -1
	s_bcnt1_i32_b64 s61, s[18:19]
	s_add_u32 s92, s92, s61
	s_branch .Lref_fin

.Lref_v3:
	ds_read_b32 v216, v238
	ds_read_u16 v224, v245
	ds_read_b32 v217, v238 offset:256
	ds_read_u16 v225, v245 offset:128
	ds_read_b32 v218, v238 offset:512
	ds_read_u16 v226, v245 offset:256
	v_cmp_gt_u32_e64 s[8:9], s93, v145
	v_add_u32_e32 v241, 64, v145
	v_cmp_gt_u32_e64 s[12:13], s93, v241
	v_add_u32_e32 v241, 128, v145
	v_cmp_gt_u32_e64 s[14:15], s93, v241
	s_waitcnt lgkmcnt(0)
	v_cndmask_b32_e64 v216, 0, v216, s[8:9]
	v_cndmask_b32_e64 v217, 0, v217, s[12:13]
	v_cndmask_b32_e64 v218, 0, v218, s[14:15]
	s_or_b32 s57, s33, 0x100000
	v_cmp_ge_u32_e64 s[8:9], v216, s57
	v_cmp_ge_u32_e64 s[12:13], v217, s57
	v_cmp_ge_u32_e64 s[14:15], v218, s57
	s_bcnt1_i32_b64 s89, s[8:9]
	s_bcnt1_i32_b64 s61, s[12:13]
	s_add_u32 s89, s89, s61
	s_bcnt1_i32_b64 s61, s[14:15]
	s_add_u32 s89, s89, s61
	s_cmp_ge_u32 s89, s91
	s_cselect_b32 s33, s57, s33
	s_or_b32 s57, s33, 0x80000
	v_cmp_ge_u32_e64 s[8:9], v216, s57
	v_cmp_ge_u32_e64 s[12:13], v217, s57
	v_cmp_ge_u32_e64 s[14:15], v218, s57
	s_bcnt1_i32_b64 s89, s[8:9]
	s_bcnt1_i32_b64 s61, s[12:13]
	s_add_u32 s89, s89, s61
	s_bcnt1_i32_b64 s61, s[14:15]
	s_add_u32 s89, s89, s61
	s_cmp_ge_u32 s89, s91
	s_cselect_b32 s33, s57, s33
	s_or_b32 s57, s33, 0x40000
	v_cmp_ge_u32_e64 s[8:9], v216, s57
	v_cmp_ge_u32_e64 s[12:13], v217, s57
	v_cmp_ge_u32_e64 s[14:15], v218, s57
	s_bcnt1_i32_b64 s89, s[8:9]
	s_bcnt1_i32_b64 s61, s[12:13]
	s_add_u32 s89, s89, s61
	s_bcnt1_i32_b64 s61, s[14:15]
	s_add_u32 s89, s89, s61
	s_cmp_ge_u32 s89, s91
	s_cselect_b32 s33, s57, s33
	s_or_b32 s57, s33, 0x20000
	v_cmp_ge_u32_e64 s[8:9], v216, s57
	v_cmp_ge_u32_e64 s[12:13], v217, s57
	v_cmp_ge_u32_e64 s[14:15], v218, s57
	s_bcnt1_i32_b64 s89, s[8:9]
	s_bcnt1_i32_b64 s61, s[12:13]
	s_add_u32 s89, s89, s61
	s_bcnt1_i32_b64 s61, s[14:15]
	s_add_u32 s89, s89, s61
	s_cmp_ge_u32 s89, s91
	s_cselect_b32 s33, s57, s33
	s_or_b32 s57, s33, 0x10000
	v_cmp_ge_u32_e64 s[8:9], v216, s57
	v_cmp_ge_u32_e64 s[12:13], v217, s57
	v_cmp_ge_u32_e64 s[14:15], v218, s57
	s_bcnt1_i32_b64 s89, s[8:9]
	s_bcnt1_i32_b64 s61, s[12:13]
	s_add_u32 s89, s89, s61
	s_bcnt1_i32_b64 s61, s[14:15]
	s_add_u32 s89, s89, s61
	s_cmp_ge_u32 s89, s91
	s_cselect_b32 s33, s57, s33
	s_or_b32 s57, s33, 0x8000
	v_cmp_ge_u32_e64 s[8:9], v216, s57
	v_cmp_ge_u32_e64 s[12:13], v217, s57
	v_cmp_ge_u32_e64 s[14:15], v218, s57
	s_bcnt1_i32_b64 s89, s[8:9]
	s_bcnt1_i32_b64 s61, s[12:13]
	s_add_u32 s89, s89, s61
	s_bcnt1_i32_b64 s61, s[14:15]
	s_add_u32 s89, s89, s61
	s_cmp_ge_u32 s89, s91
	s_cselect_b32 s33, s57, s33
	s_or_b32 s57, s33, 0x4000
	v_cmp_ge_u32_e64 s[8:9], v216, s57
	v_cmp_ge_u32_e64 s[12:13], v217, s57
	v_cmp_ge_u32_e64 s[14:15], v218, s57
	s_bcnt1_i32_b64 s89, s[8:9]
	s_bcnt1_i32_b64 s61, s[12:13]
	s_add_u32 s89, s89, s61
	s_bcnt1_i32_b64 s61, s[14:15]
	s_add_u32 s89, s89, s61
	s_cmp_ge_u32 s89, s91
	s_cselect_b32 s33, s57, s33
	s_or_b32 s57, s33, 0x2000
	v_cmp_ge_u32_e64 s[8:9], v216, s57
	v_cmp_ge_u32_e64 s[12:13], v217, s57
	v_cmp_ge_u32_e64 s[14:15], v218, s57
	s_bcnt1_i32_b64 s89, s[8:9]
	s_bcnt1_i32_b64 s61, s[12:13]
	s_add_u32 s89, s89, s61
	s_bcnt1_i32_b64 s61, s[14:15]
	s_add_u32 s89, s89, s61
	s_cmp_ge_u32 s89, s91
	s_cselect_b32 s33, s57, s33
	s_or_b32 s57, s33, 0x1000
	v_cmp_ge_u32_e64 s[8:9], v216, s57
	v_cmp_ge_u32_e64 s[12:13], v217, s57
	v_cmp_ge_u32_e64 s[14:15], v218, s57
	s_bcnt1_i32_b64 s89, s[8:9]
	s_bcnt1_i32_b64 s61, s[12:13]
	s_add_u32 s89, s89, s61
	s_bcnt1_i32_b64 s61, s[14:15]
	s_add_u32 s89, s89, s61
	s_cmp_ge_u32 s89, s91
	s_cselect_b32 s33, s57, s33
	s_or_b32 s57, s33, 0x800
	v_cmp_ge_u32_e64 s[8:9], v216, s57
	v_cmp_ge_u32_e64 s[12:13], v217, s57
	v_cmp_ge_u32_e64 s[14:15], v218, s57
	s_bcnt1_i32_b64 s89, s[8:9]
	s_bcnt1_i32_b64 s61, s[12:13]
	s_add_u32 s89, s89, s61
	s_bcnt1_i32_b64 s61, s[14:15]
	s_add_u32 s89, s89, s61
	s_cmp_ge_u32 s89, s91
	s_cselect_b32 s33, s57, s33
	s_or_b32 s57, s33, 0x400
	v_cmp_ge_u32_e64 s[8:9], v216, s57
	v_cmp_ge_u32_e64 s[12:13], v217, s57
	v_cmp_ge_u32_e64 s[14:15], v218, s57
	s_bcnt1_i32_b64 s89, s[8:9]
	s_bcnt1_i32_b64 s61, s[12:13]
	s_add_u32 s89, s89, s61
	s_bcnt1_i32_b64 s61, s[14:15]
	s_add_u32 s89, s89, s61
	s_cmp_ge_u32 s89, s91
	s_cselect_b32 s33, s57, s33
	s_or_b32 s57, s33, 0x200
	v_cmp_ge_u32_e64 s[8:9], v216, s57
	v_cmp_ge_u32_e64 s[12:13], v217, s57
	v_cmp_ge_u32_e64 s[14:15], v218, s57
	s_bcnt1_i32_b64 s89, s[8:9]
	s_bcnt1_i32_b64 s61, s[12:13]
	s_add_u32 s89, s89, s61
	s_bcnt1_i32_b64 s61, s[14:15]
	s_add_u32 s89, s89, s61
	s_cmp_ge_u32 s89, s91
	s_cselect_b32 s33, s57, s33
	s_or_b32 s57, s33, 0x100
	v_cmp_ge_u32_e64 s[8:9], v216, s57
	v_cmp_ge_u32_e64 s[12:13], v217, s57
	v_cmp_ge_u32_e64 s[14:15], v218, s57
	s_bcnt1_i32_b64 s89, s[8:9]
	s_bcnt1_i32_b64 s61, s[12:13]
	s_add_u32 s89, s89, s61
	s_bcnt1_i32_b64 s61, s[14:15]
	s_add_u32 s89, s89, s61
	s_cmp_ge_u32 s89, s91
	s_cselect_b32 s33, s57, s33
	s_or_b32 s57, s33, 0x80
	v_cmp_ge_u32_e64 s[8:9], v216, s57
	v_cmp_ge_u32_e64 s[12:13], v217, s57
	v_cmp_ge_u32_e64 s[14:15], v218, s57
	s_bcnt1_i32_b64 s89, s[8:9]
	s_bcnt1_i32_b64 s61, s[12:13]
	s_add_u32 s89, s89, s61
	s_bcnt1_i32_b64 s61, s[14:15]
	s_add_u32 s89, s89, s61
	s_cmp_ge_u32 s89, s91
	s_cselect_b32 s33, s57, s33
	s_or_b32 s57, s33, 0x40
	v_cmp_ge_u32_e64 s[8:9], v216, s57
	v_cmp_ge_u32_e64 s[12:13], v217, s57
	v_cmp_ge_u32_e64 s[14:15], v218, s57
	s_bcnt1_i32_b64 s89, s[8:9]
	s_bcnt1_i32_b64 s61, s[12:13]
	s_add_u32 s89, s89, s61
	s_bcnt1_i32_b64 s61, s[14:15]
	s_add_u32 s89, s89, s61
	s_cmp_ge_u32 s89, s91
	s_cselect_b32 s33, s57, s33
	s_or_b32 s57, s33, 0x20
	v_cmp_ge_u32_e64 s[8:9], v216, s57
	v_cmp_ge_u32_e64 s[12:13], v217, s57
	v_cmp_ge_u32_e64 s[14:15], v218, s57
	s_bcnt1_i32_b64 s89, s[8:9]
	s_bcnt1_i32_b64 s61, s[12:13]
	s_add_u32 s89, s89, s61
	s_bcnt1_i32_b64 s61, s[14:15]
	s_add_u32 s89, s89, s61
	s_cmp_ge_u32 s89, s91
	s_cselect_b32 s33, s57, s33
	s_or_b32 s57, s33, 0x10
	v_cmp_ge_u32_e64 s[8:9], v216, s57
	v_cmp_ge_u32_e64 s[12:13], v217, s57
	v_cmp_ge_u32_e64 s[14:15], v218, s57
	s_bcnt1_i32_b64 s89, s[8:9]
	s_bcnt1_i32_b64 s61, s[12:13]
	s_add_u32 s89, s89, s61
	s_bcnt1_i32_b64 s61, s[14:15]
	s_add_u32 s89, s89, s61
	s_cmp_ge_u32 s89, s91
	s_cselect_b32 s33, s57, s33
	s_or_b32 s57, s33, 0x8
	v_cmp_ge_u32_e64 s[8:9], v216, s57
	v_cmp_ge_u32_e64 s[12:13], v217, s57
	v_cmp_ge_u32_e64 s[14:15], v218, s57
	s_bcnt1_i32_b64 s89, s[8:9]
	s_bcnt1_i32_b64 s61, s[12:13]
	s_add_u32 s89, s89, s61
	s_bcnt1_i32_b64 s61, s[14:15]
	s_add_u32 s89, s89, s61
	s_cmp_ge_u32 s89, s91
	s_cselect_b32 s33, s57, s33
	s_or_b32 s57, s33, 0x4
	v_cmp_ge_u32_e64 s[8:9], v216, s57
	v_cmp_ge_u32_e64 s[12:13], v217, s57
	v_cmp_ge_u32_e64 s[14:15], v218, s57
	s_bcnt1_i32_b64 s89, s[8:9]
	s_bcnt1_i32_b64 s61, s[12:13]
	s_add_u32 s89, s89, s61
	s_bcnt1_i32_b64 s61, s[14:15]
	s_add_u32 s89, s89, s61
	s_cmp_ge_u32 s89, s91
	s_cselect_b32 s33, s57, s33
	s_or_b32 s57, s33, 0x2
	v_cmp_ge_u32_e64 s[8:9], v216, s57
	v_cmp_ge_u32_e64 s[12:13], v217, s57
	v_cmp_ge_u32_e64 s[14:15], v218, s57
	s_bcnt1_i32_b64 s89, s[8:9]
	s_bcnt1_i32_b64 s61, s[12:13]
	s_add_u32 s89, s89, s61
	s_bcnt1_i32_b64 s61, s[14:15]
	s_add_u32 s89, s89, s61
	s_cmp_ge_u32 s89, s91
	s_cselect_b32 s33, s57, s33
	s_or_b32 s57, s33, 0x1
	v_cmp_ge_u32_e64 s[8:9], v216, s57
	v_cmp_ge_u32_e64 s[12:13], v217, s57
	v_cmp_ge_u32_e64 s[14:15], v218, s57
	s_bcnt1_i32_b64 s89, s[8:9]
	s_bcnt1_i32_b64 s61, s[12:13]
	s_add_u32 s89, s89, s61
	s_bcnt1_i32_b64 s61, s[14:15]
	s_add_u32 s89, s89, s61
	s_cmp_ge_u32 s89, s91
	s_cselect_b32 s33, s57, s33
	v_cmp_gt_u32_e64 s[8:9], v216, s33
	v_cmp_gt_u32_e64 s[12:13], v217, s33
	v_cmp_gt_u32_e64 s[14:15], v218, s33
	s_bcnt1_i32_b64 s89, s[8:9]
	s_bcnt1_i32_b64 s61, s[12:13]
	s_add_u32 s89, s89, s61
	s_bcnt1_i32_b64 s61, s[14:15]
	s_add_u32 s89, s89, s61
	s_sub_u32 s91, s91, s89
	v_cmp_eq_u32_e64 s[8:9], v216, s33
	v_cmp_eq_u32_e64 s[12:13], v217, s33
	v_cmp_eq_u32_e64 s[14:15], v218, s33
	s_bcnt1_i32_b64 s89, s[8:9]
	s_bcnt1_i32_b64 s61, s[12:13]
	s_add_u32 s89, s89, s61
	s_bcnt1_i32_b64 s61, s[14:15]
	s_add_u32 s89, s89, s61
	s_add_u32 s57, s33, 1
	s_cmp_eq_u32 s91, s89
	s_cselect_b32 s57, s33, s57
	s_cselect_b32 s60, 1, 0
	v_cmp_ge_u32_e64 s[8:9], v216, s57
	v_cmp_ge_u32_e64 s[12:13], v217, s57
	v_cmp_ge_u32_e64 s[14:15], v218, s57
	s_nop 1
	v_mbcnt_lo_u32_b32 v241, s8, 0
	v_mbcnt_hi_u32_b32 v241, s9, v241
	v_add_u32_e32 v241, s90, v241
	v_and_b32_e32 v241, 0xff, v241
	v_lshl_add_u32 v241, v241, 1, v246
	s_mov_b64 exec, s[8:9]
	ds_write_b16 v241, v224
	s_mov_b64 exec, -1
	s_bcnt1_i32_b64 s61, s[8:9]
	s_add_u32 s90, s90, s61
	v_mbcnt_lo_u32_b32 v241, s12, 0
	v_mbcnt_hi_u32_b32 v241, s13, v241
	v_add_u32_e32 v241, s90, v241
	v_and_b32_e32 v241, 0xff, v241
	v_lshl_add_u32 v241, v241, 1, v246
	s_mov_b64 exec, s[12:13]
	ds_write_b16 v241, v225
	s_mov_b64 exec, -1
	s_bcnt1_i32_b64 s61, s[12:13]
	s_add_u32 s90, s90, s61
	v_mbcnt_lo_u32_b32 v241, s14, 0
	v_mbcnt_hi_u32_b32 v241, s15, v241
	v_add_u32_e32 v241, s90, v241
	v_and_b32_e32 v241, 0xff, v241
	v_lshl_add_u32 v241, v241, 1, v246
	s_mov_b64 exec, s[14:15]
	ds_write_b16 v241, v226
	s_mov_b64 exec, -1
	s_bcnt1_i32_b64 s61, s[14:15]
	s_add_u32 s90, s90, s61
	s_mov_b32 s92, 0
	s_cmp_lg_u32 s60, 0
	s_cbranch_scc1 .Lref_fin
	v_cmp_eq_u32_e64 s[8:9], v216, s33
	v_cmp_eq_u32_e64 s[12:13], v217, s33
	v_cmp_eq_u32_e64 s[14:15], v218, s33
	s_nop 1
	v_mbcnt_lo_u32_b32 v241, s8, 0
	v_mbcnt_hi_u32_b32 v241, s9, v241
	v_add_u32_e32 v241, s92, v241
	v_lshl_add_u32 v241, v241, 1, v244
	s_mov_b64 exec, s[8:9]
	ds_write_b16 v241, v224
	s_mov_b64 exec, -1
	s_bcnt1_i32_b64 s61, s[8:9]
	s_add_u32 s92, s92, s61
	v_mbcnt_lo_u32_b32 v241, s12, 0
	v_mbcnt_hi_u32_b32 v241, s13, v241
	v_add_u32_e32 v241, s92, v241
	v_lshl_add_u32 v241, v241, 1, v244
	s_mov_b64 exec, s[12:13]
	ds_write_b16 v241, v225
	s_mov_b64 exec, -1
	s_bcnt1_i32_b64 s61, s[12:13]
	s_add_u32 s92, s92, s61
	v_mbcnt_lo_u32_b32 v241, s14, 0
	v_mbcnt_hi_u32_b32 v241, s15, v241
	v_add_u32_e32 v241, s92, v241
	v_lshl_add_u32 v241, v241, 1, v244
	s_mov_b64 exec, s[14:15]
	ds_write_b16 v241, v226
	s_mov_b64 exec, -1
	s_bcnt1_i32_b64 s61, s[14:15]
	s_add_u32 s92, s92, s61
	s_branch .Lref_fin
.Lref_v2:
	ds_read_b32 v216, v238
	ds_read_u16 v224, v245
	ds_read_b32 v217, v238 offset:256
	ds_read_u16 v225, v245 offset:128
	v_cmp_gt_u32_e64 s[8:9], s93, v145
	v_add_u32_e32 v241, 64, v145
	v_cmp_gt_u32_e64 s[12:13], s93, v241
	s_waitcnt lgkmcnt(0)
	v_cndmask_b32_e64 v216, 0, v216, s[8:9]
	v_cndmask_b32_e64 v217, 0, v217, s[12:13]
	s_or_b32 s57, s33, 0x100000
	v_cmp_ge_u32_e64 s[8:9], v216, s57
	v_cmp_ge_u32_e64 s[12:13], v217, s57
	s_bcnt1_i32_b64 s89, s[8:9]
	s_bcnt1_i32_b64 s61, s[12:13]
	s_add_u32 s89, s89, s61
	s_cmp_ge_u32 s89, s91
	s_cselect_b32 s33, s57, s33
	s_or_b32 s57, s33, 0x80000
	v_cmp_ge_u32_e64 s[8:9], v216, s57
	v_cmp_ge_u32_e64 s[12:13], v217, s57
	s_bcnt1_i32_b64 s89, s[8:9]
	s_bcnt1_i32_b64 s61, s[12:13]
	s_add_u32 s89, s89, s61
	s_cmp_ge_u32 s89, s91
	s_cselect_b32 s33, s57, s33
	s_or_b32 s57, s33, 0x40000
	v_cmp_ge_u32_e64 s[8:9], v216, s57
	v_cmp_ge_u32_e64 s[12:13], v217, s57
	s_bcnt1_i32_b64 s89, s[8:9]
	s_bcnt1_i32_b64 s61, s[12:13]
	s_add_u32 s89, s89, s61
	s_cmp_ge_u32 s89, s91
	s_cselect_b32 s33, s57, s33
	s_or_b32 s57, s33, 0x20000
	v_cmp_ge_u32_e64 s[8:9], v216, s57
	v_cmp_ge_u32_e64 s[12:13], v217, s57
	s_bcnt1_i32_b64 s89, s[8:9]
	s_bcnt1_i32_b64 s61, s[12:13]
	s_add_u32 s89, s89, s61
	s_cmp_ge_u32 s89, s91
	s_cselect_b32 s33, s57, s33
	s_or_b32 s57, s33, 0x10000
	v_cmp_ge_u32_e64 s[8:9], v216, s57
	v_cmp_ge_u32_e64 s[12:13], v217, s57
	s_bcnt1_i32_b64 s89, s[8:9]
	s_bcnt1_i32_b64 s61, s[12:13]
	s_add_u32 s89, s89, s61
	s_cmp_ge_u32 s89, s91
	s_cselect_b32 s33, s57, s33
	s_or_b32 s57, s33, 0x8000
	v_cmp_ge_u32_e64 s[8:9], v216, s57
	v_cmp_ge_u32_e64 s[12:13], v217, s57
	s_bcnt1_i32_b64 s89, s[8:9]
	s_bcnt1_i32_b64 s61, s[12:13]
	s_add_u32 s89, s89, s61
	s_cmp_ge_u32 s89, s91
	s_cselect_b32 s33, s57, s33
	s_or_b32 s57, s33, 0x4000
	v_cmp_ge_u32_e64 s[8:9], v216, s57
	v_cmp_ge_u32_e64 s[12:13], v217, s57
	s_bcnt1_i32_b64 s89, s[8:9]
	s_bcnt1_i32_b64 s61, s[12:13]
	s_add_u32 s89, s89, s61
	s_cmp_ge_u32 s89, s91
	s_cselect_b32 s33, s57, s33
	s_or_b32 s57, s33, 0x2000
	v_cmp_ge_u32_e64 s[8:9], v216, s57
	v_cmp_ge_u32_e64 s[12:13], v217, s57
	s_bcnt1_i32_b64 s89, s[8:9]
	s_bcnt1_i32_b64 s61, s[12:13]
	s_add_u32 s89, s89, s61
	s_cmp_ge_u32 s89, s91
	s_cselect_b32 s33, s57, s33
	s_or_b32 s57, s33, 0x1000
	v_cmp_ge_u32_e64 s[8:9], v216, s57
	v_cmp_ge_u32_e64 s[12:13], v217, s57
	s_bcnt1_i32_b64 s89, s[8:9]
	s_bcnt1_i32_b64 s61, s[12:13]
	s_add_u32 s89, s89, s61
	s_cmp_ge_u32 s89, s91
	s_cselect_b32 s33, s57, s33
	s_or_b32 s57, s33, 0x800
	v_cmp_ge_u32_e64 s[8:9], v216, s57
	v_cmp_ge_u32_e64 s[12:13], v217, s57
	s_bcnt1_i32_b64 s89, s[8:9]
	s_bcnt1_i32_b64 s61, s[12:13]
	s_add_u32 s89, s89, s61
	s_cmp_ge_u32 s89, s91
	s_cselect_b32 s33, s57, s33
	s_or_b32 s57, s33, 0x400
	v_cmp_ge_u32_e64 s[8:9], v216, s57
	v_cmp_ge_u32_e64 s[12:13], v217, s57
	s_bcnt1_i32_b64 s89, s[8:9]
	s_bcnt1_i32_b64 s61, s[12:13]
	s_add_u32 s89, s89, s61
	s_cmp_ge_u32 s89, s91
	s_cselect_b32 s33, s57, s33
	s_or_b32 s57, s33, 0x200
	v_cmp_ge_u32_e64 s[8:9], v216, s57
	v_cmp_ge_u32_e64 s[12:13], v217, s57
	s_bcnt1_i32_b64 s89, s[8:9]
	s_bcnt1_i32_b64 s61, s[12:13]
	s_add_u32 s89, s89, s61
	s_cmp_ge_u32 s89, s91
	s_cselect_b32 s33, s57, s33
	s_or_b32 s57, s33, 0x100
	v_cmp_ge_u32_e64 s[8:9], v216, s57
	v_cmp_ge_u32_e64 s[12:13], v217, s57
	s_bcnt1_i32_b64 s89, s[8:9]
	s_bcnt1_i32_b64 s61, s[12:13]
	s_add_u32 s89, s89, s61
	s_cmp_ge_u32 s89, s91
	s_cselect_b32 s33, s57, s33
	s_or_b32 s57, s33, 0x80
	v_cmp_ge_u32_e64 s[8:9], v216, s57
	v_cmp_ge_u32_e64 s[12:13], v217, s57
	s_bcnt1_i32_b64 s89, s[8:9]
	s_bcnt1_i32_b64 s61, s[12:13]
	s_add_u32 s89, s89, s61
	s_cmp_ge_u32 s89, s91
	s_cselect_b32 s33, s57, s33
	s_or_b32 s57, s33, 0x40
	v_cmp_ge_u32_e64 s[8:9], v216, s57
	v_cmp_ge_u32_e64 s[12:13], v217, s57
	s_bcnt1_i32_b64 s89, s[8:9]
	s_bcnt1_i32_b64 s61, s[12:13]
	s_add_u32 s89, s89, s61
	s_cmp_ge_u32 s89, s91
	s_cselect_b32 s33, s57, s33
	s_or_b32 s57, s33, 0x20
	v_cmp_ge_u32_e64 s[8:9], v216, s57
	v_cmp_ge_u32_e64 s[12:13], v217, s57
	s_bcnt1_i32_b64 s89, s[8:9]
	s_bcnt1_i32_b64 s61, s[12:13]
	s_add_u32 s89, s89, s61
	s_cmp_ge_u32 s89, s91
	s_cselect_b32 s33, s57, s33
	s_or_b32 s57, s33, 0x10
	v_cmp_ge_u32_e64 s[8:9], v216, s57
	v_cmp_ge_u32_e64 s[12:13], v217, s57
	s_bcnt1_i32_b64 s89, s[8:9]
	s_bcnt1_i32_b64 s61, s[12:13]
	s_add_u32 s89, s89, s61
	s_cmp_ge_u32 s89, s91
	s_cselect_b32 s33, s57, s33
	s_or_b32 s57, s33, 0x8
	v_cmp_ge_u32_e64 s[8:9], v216, s57
	v_cmp_ge_u32_e64 s[12:13], v217, s57
	s_bcnt1_i32_b64 s89, s[8:9]
	s_bcnt1_i32_b64 s61, s[12:13]
	s_add_u32 s89, s89, s61
	s_cmp_ge_u32 s89, s91
	s_cselect_b32 s33, s57, s33
	s_or_b32 s57, s33, 0x4
	v_cmp_ge_u32_e64 s[8:9], v216, s57
	v_cmp_ge_u32_e64 s[12:13], v217, s57
	s_bcnt1_i32_b64 s89, s[8:9]
	s_bcnt1_i32_b64 s61, s[12:13]
	s_add_u32 s89, s89, s61
	s_cmp_ge_u32 s89, s91
	s_cselect_b32 s33, s57, s33
	s_or_b32 s57, s33, 0x2
	v_cmp_ge_u32_e64 s[8:9], v216, s57
	v_cmp_ge_u32_e64 s[12:13], v217, s57
	s_bcnt1_i32_b64 s89, s[8:9]
	s_bcnt1_i32_b64 s61, s[12:13]
	s_add_u32 s89, s89, s61
	s_cmp_ge_u32 s89, s91
	s_cselect_b32 s33, s57, s33
	s_or_b32 s57, s33, 0x1
	v_cmp_ge_u32_e64 s[8:9], v216, s57
	v_cmp_ge_u32_e64 s[12:13], v217, s57
	s_bcnt1_i32_b64 s89, s[8:9]
	s_bcnt1_i32_b64 s61, s[12:13]
	s_add_u32 s89, s89, s61
	s_cmp_ge_u32 s89, s91
	s_cselect_b32 s33, s57, s33
	v_cmp_gt_u32_e64 s[8:9], v216, s33
	v_cmp_gt_u32_e64 s[12:13], v217, s33
	s_bcnt1_i32_b64 s89, s[8:9]
	s_bcnt1_i32_b64 s61, s[12:13]
	s_add_u32 s89, s89, s61
	s_sub_u32 s91, s91, s89
	v_cmp_eq_u32_e64 s[8:9], v216, s33
	v_cmp_eq_u32_e64 s[12:13], v217, s33
	s_bcnt1_i32_b64 s89, s[8:9]
	s_bcnt1_i32_b64 s61, s[12:13]
	s_add_u32 s89, s89, s61
	s_add_u32 s57, s33, 1
	s_cmp_eq_u32 s91, s89
	s_cselect_b32 s57, s33, s57
	s_cselect_b32 s60, 1, 0
	v_cmp_ge_u32_e64 s[8:9], v216, s57
	v_cmp_ge_u32_e64 s[12:13], v217, s57
	s_nop 1
	v_mbcnt_lo_u32_b32 v241, s8, 0
	v_mbcnt_hi_u32_b32 v241, s9, v241
	v_add_u32_e32 v241, s90, v241
	v_and_b32_e32 v241, 0xff, v241
	v_lshl_add_u32 v241, v241, 1, v246
	s_mov_b64 exec, s[8:9]
	ds_write_b16 v241, v224
	s_mov_b64 exec, -1
	s_bcnt1_i32_b64 s61, s[8:9]
	s_add_u32 s90, s90, s61
	v_mbcnt_lo_u32_b32 v241, s12, 0
	v_mbcnt_hi_u32_b32 v241, s13, v241
	v_add_u32_e32 v241, s90, v241
	v_and_b32_e32 v241, 0xff, v241
	v_lshl_add_u32 v241, v241, 1, v246
	s_mov_b64 exec, s[12:13]
	ds_write_b16 v241, v225
	s_mov_b64 exec, -1
	s_bcnt1_i32_b64 s61, s[12:13]
	s_add_u32 s90, s90, s61
	s_mov_b32 s92, 0
	s_cmp_lg_u32 s60, 0
	s_cbranch_scc1 .Lref_fin
	v_cmp_eq_u32_e64 s[8:9], v216, s33
	v_cmp_eq_u32_e64 s[12:13], v217, s33
	s_nop 1
	v_mbcnt_lo_u32_b32 v241, s8, 0
	v_mbcnt_hi_u32_b32 v241, s9, v241
	v_add_u32_e32 v241, s92, v241
	v_lshl_add_u32 v241, v241, 1, v244
	s_mov_b64 exec, s[8:9]
	ds_write_b16 v241, v224
	s_mov_b64 exec, -1
	s_bcnt1_i32_b64 s61, s[8:9]
	s_add_u32 s92, s92, s61
	v_mbcnt_lo_u32_b32 v241, s12, 0
	v_mbcnt_hi_u32_b32 v241, s13, v241
	v_add_u32_e32 v241, s92, v241
	v_lshl_add_u32 v241, v241, 1, v244
	s_mov_b64 exec, s[12:13]
	ds_write_b16 v241, v225
	s_mov_b64 exec, -1
	s_bcnt1_i32_b64 s61, s[12:13]
	s_add_u32 s92, s92, s61
	s_branch .Lref_fin
.Lref_v1:
	ds_read_b32 v216, v238
	ds_read_u16 v224, v245
	v_cmp_gt_u32_e64 s[8:9], s93, v145
	s_waitcnt lgkmcnt(0)
	v_cndmask_b32_e64 v216, 0, v216, s[8:9]
	s_or_b32 s57, s33, 0x100000
	v_cmp_ge_u32_e64 s[8:9], v216, s57
	s_bcnt1_i32_b64 s89, s[8:9]
	s_cmp_ge_u32 s89, s91
	s_cselect_b32 s33, s57, s33
	s_or_b32 s57, s33, 0x80000
	v_cmp_ge_u32_e64 s[8:9], v216, s57
	s_bcnt1_i32_b64 s89, s[8:9]
	s_cmp_ge_u32 s89, s91
	s_cselect_b32 s33, s57, s33
	s_or_b32 s57, s33, 0x40000
	v_cmp_ge_u32_e64 s[8:9], v216, s57
	s_bcnt1_i32_b64 s89, s[8:9]
	s_cmp_ge_u32 s89, s91
	s_cselect_b32 s33, s57, s33
	s_or_b32 s57, s33, 0x20000
	v_cmp_ge_u32_e64 s[8:9], v216, s57
	s_bcnt1_i32_b64 s89, s[8:9]
	s_cmp_ge_u32 s89, s91
	s_cselect_b32 s33, s57, s33
	s_or_b32 s57, s33, 0x10000
	v_cmp_ge_u32_e64 s[8:9], v216, s57
	s_bcnt1_i32_b64 s89, s[8:9]
	s_cmp_ge_u32 s89, s91
	s_cselect_b32 s33, s57, s33
	s_or_b32 s57, s33, 0x8000
	v_cmp_ge_u32_e64 s[8:9], v216, s57
	s_bcnt1_i32_b64 s89, s[8:9]
	s_cmp_ge_u32 s89, s91
	s_cselect_b32 s33, s57, s33
	s_or_b32 s57, s33, 0x4000
	v_cmp_ge_u32_e64 s[8:9], v216, s57
	s_bcnt1_i32_b64 s89, s[8:9]
	s_cmp_ge_u32 s89, s91
	s_cselect_b32 s33, s57, s33
	s_or_b32 s57, s33, 0x2000
	v_cmp_ge_u32_e64 s[8:9], v216, s57
	s_bcnt1_i32_b64 s89, s[8:9]
	s_cmp_ge_u32 s89, s91
	s_cselect_b32 s33, s57, s33
	s_or_b32 s57, s33, 0x1000
	v_cmp_ge_u32_e64 s[8:9], v216, s57
	s_bcnt1_i32_b64 s89, s[8:9]
	s_cmp_ge_u32 s89, s91
	s_cselect_b32 s33, s57, s33
	s_or_b32 s57, s33, 0x800
	v_cmp_ge_u32_e64 s[8:9], v216, s57
	s_bcnt1_i32_b64 s89, s[8:9]
	s_cmp_ge_u32 s89, s91
	s_cselect_b32 s33, s57, s33
	s_or_b32 s57, s33, 0x400
	v_cmp_ge_u32_e64 s[8:9], v216, s57
	s_bcnt1_i32_b64 s89, s[8:9]
	s_cmp_ge_u32 s89, s91
	s_cselect_b32 s33, s57, s33
	s_or_b32 s57, s33, 0x200
	v_cmp_ge_u32_e64 s[8:9], v216, s57
	s_bcnt1_i32_b64 s89, s[8:9]
	s_cmp_ge_u32 s89, s91
	s_cselect_b32 s33, s57, s33
	s_or_b32 s57, s33, 0x100
	v_cmp_ge_u32_e64 s[8:9], v216, s57
	s_bcnt1_i32_b64 s89, s[8:9]
	s_cmp_ge_u32 s89, s91
	s_cselect_b32 s33, s57, s33
	s_or_b32 s57, s33, 0x80
	v_cmp_ge_u32_e64 s[8:9], v216, s57
	s_bcnt1_i32_b64 s89, s[8:9]
	s_cmp_ge_u32 s89, s91
	s_cselect_b32 s33, s57, s33
	s_or_b32 s57, s33, 0x40
	v_cmp_ge_u32_e64 s[8:9], v216, s57
	s_bcnt1_i32_b64 s89, s[8:9]
	s_cmp_ge_u32 s89, s91
	s_cselect_b32 s33, s57, s33
	s_or_b32 s57, s33, 0x20
	v_cmp_ge_u32_e64 s[8:9], v216, s57
	s_bcnt1_i32_b64 s89, s[8:9]
	s_cmp_ge_u32 s89, s91
	s_cselect_b32 s33, s57, s33
	s_or_b32 s57, s33, 0x10
	v_cmp_ge_u32_e64 s[8:9], v216, s57
	s_bcnt1_i32_b64 s89, s[8:9]
	s_cmp_ge_u32 s89, s91
	s_cselect_b32 s33, s57, s33
	s_or_b32 s57, s33, 0x8
	v_cmp_ge_u32_e64 s[8:9], v216, s57
	s_bcnt1_i32_b64 s89, s[8:9]
	s_cmp_ge_u32 s89, s91
	s_cselect_b32 s33, s57, s33
	s_or_b32 s57, s33, 0x4
	v_cmp_ge_u32_e64 s[8:9], v216, s57
	s_bcnt1_i32_b64 s89, s[8:9]
	s_cmp_ge_u32 s89, s91
	s_cselect_b32 s33, s57, s33
	s_or_b32 s57, s33, 0x2
	v_cmp_ge_u32_e64 s[8:9], v216, s57
	s_bcnt1_i32_b64 s89, s[8:9]
	s_cmp_ge_u32 s89, s91
	s_cselect_b32 s33, s57, s33
	s_or_b32 s57, s33, 0x1
	v_cmp_ge_u32_e64 s[8:9], v216, s57
	s_bcnt1_i32_b64 s89, s[8:9]
	s_cmp_ge_u32 s89, s91
	s_cselect_b32 s33, s57, s33
	v_cmp_gt_u32_e64 s[8:9], v216, s33
	s_bcnt1_i32_b64 s89, s[8:9]
	s_sub_u32 s91, s91, s89
	v_cmp_eq_u32_e64 s[8:9], v216, s33
	s_bcnt1_i32_b64 s89, s[8:9]
	s_add_u32 s57, s33, 1
	s_cmp_eq_u32 s91, s89
	s_cselect_b32 s57, s33, s57
	s_cselect_b32 s60, 1, 0
	v_cmp_ge_u32_e64 s[8:9], v216, s57
	s_nop 1
	v_mbcnt_lo_u32_b32 v241, s8, 0
	v_mbcnt_hi_u32_b32 v241, s9, v241
	v_add_u32_e32 v241, s90, v241
	v_and_b32_e32 v241, 0xff, v241
	v_lshl_add_u32 v241, v241, 1, v246
	s_mov_b64 exec, s[8:9]
	ds_write_b16 v241, v224
	s_mov_b64 exec, -1
	s_bcnt1_i32_b64 s61, s[8:9]
	s_add_u32 s90, s90, s61
	s_mov_b32 s92, 0
	s_cmp_lg_u32 s60, 0
	s_cbranch_scc1 .Lref_fin
	v_cmp_eq_u32_e64 s[8:9], v216, s33
	s_nop 1
	v_mbcnt_lo_u32_b32 v241, s8, 0
	v_mbcnt_hi_u32_b32 v241, s9, v241
	v_add_u32_e32 v241, s92, v241
	v_lshl_add_u32 v241, v241, 1, v244
	s_mov_b64 exec, s[8:9]
	ds_write_b16 v241, v224
	s_mov_b64 exec, -1
	s_bcnt1_i32_b64 s61, s[8:9]
	s_add_u32 s92, s92, s61

.LBB0_975:
	s_or_b64 exec, exec, s[4:5]
	v_mov_b32_e32 v15, v202
	s_add_u32 s62, s28, 0x14000000
	s_waitcnt lgkmcnt(0)
	s_barrier
	s_nop 0
	s_nop 0
	s_nop 0
	s_nop 0
	s_nop 0
	s_nop 0
	s_nop 0
	s_nop 0
	s_nop 0
	s_nop 0
	s_nop 0
	s_nop 0
	s_nop 0
	s_nop 0
	s_nop 0
	s_nop 0
	s_nop 0
	s_nop 0
	s_nop 0
	s_nop 0
	s_nop 0
	s_nop 0
	s_nop 0
	s_nop 0
	s_nop 0
	s_nop 0
	s_nop 0
	s_nop 0
	s_nop 0
	s_nop 0
	s_addc_u32 s63, s29, 0
	v_readfirstlane_b32 s4, v15
	s_ashr_i32 s4, s4, 6
	s_and_b64 s[6:7], s[46:47], exec
	s_cselect_b32 s5, 8, 1
	v_cvt_f32_ubyte0_e32 v1, s5
	v_rcp_iflag_f32_e32 v1, v1
	s_add_i32 s8, s5, -1
	s_and_b64 s[6:7], s[46:47], exec
	s_cselect_b32 s24, 3, 0
	v_mul_f32_e32 v1, 0x4f7ffffe, v1
	v_cvt_u32_f32_e32 v1, v1
	s_sub_i32 s9, 0, s5
	s_abs_i32 s7, s30
	s_lshr_b32 s6, s2, s24
	v_readfirstlane_b32 s10, v1
	s_mul_i32 s9, s9, s10
	s_mul_hi_u32 s9, s10, s9
	s_add_i32 s10, s10, s9
	s_mul_hi_u32 s9, s7, s10
	s_mul_i32 s10, s9, s5
	s_sub_i32 s7, s7, s10
	s_lshl_b32 s6, s6, 3
	s_ashr_i32 s68, s30, 31
	s_add_i32 s10, s9, 1
	s_sub_i32 s11, s7, s5
	s_cmp_ge_u32 s7, s5
	s_cselect_b32 s9, s10, s9
	s_cselect_b32 s7, s11, s7
	s_add_i32 s10, s9, 1
	s_cmp_ge_u32 s7, s5
	s_cselect_b32 s7, s10, s9
	s_xor_b32 s7, s7, s68
	s_sub_i32 s7, s7, s68
	s_lshl_b32 s25, s7, 3
	s_abs_i32 s7, s25
	v_cvt_f32_u32_e32 v1, s7
	s_add_i32 s40, s4, s6
	s_sub_i32 s6, s25, s40
	s_and_b32 s41, s8, s2
	v_rcp_iflag_f32_e32 v1, v1
	s_add_i32 s8, s6, 0x1fff
	s_sub_i32 s6, 0xffffe001, s6
	s_xor_b32 s9, s8, s25
	v_mul_f32_e32 v1, 0x4f7ffffe, v1
	v_cvt_u32_f32_e32 v1, v1
	s_max_i32 s6, s8, s6
	s_sub_i32 s8, 0, s7
	s_ashr_i32 s9, s9, 31
	v_readfirstlane_b32 s10, v1
	s_mul_i32 s8, s8, s10
	s_mul_hi_u32 s8, s10, s8
	s_add_i32 s10, s10, s8
	s_mul_hi_u32 s8, s6, s10
	s_mul_i32 s10, s8, s7
	s_sub_i32 s6, s6, s10
	s_add_i32 s10, s8, 1
	s_sub_i32 s11, s6, s7
	s_cmp_ge_u32 s6, s7
	s_cselect_b32 s8, s10, s8
	s_cselect_b32 s6, s11, s6
	s_add_i32 s10, s8, 1
	s_cmp_ge_u32 s6, s7
	s_cselect_b32 s6, s10, s8
	s_sub_i32 s5, s5, s41
	s_xor_b32 s6, s6, s9
	s_add_i32 s5, s5, 15
	s_sub_i32 s42, s6, s9
	s_lshr_b32 s5, s5, s24
	s_mul_i32 s43, s42, s5
	s_cmp_lt_i32 s43, 1
	s_mov_b32 s9, 0
	s_cbranch_scc1 .LBB0_980
	s_lshl_b32 s5, s4, 14
	s_lshl_b32 s4, s4, 10
	s_add_i32 s47, s4, 0
	s_lshr_b32 s8, s41, 2
	s_add_i32 s46, s5, 0
	s_add_i32 s47, s47, 0x20000
	s_and_b32 s10, s41, 3
	s_lshl_b64 s[4:5], s[8:9], 13
	s_ashr_i32 s6, s40, 31
	s_add_u32 s4, s4, s40
	s_addc_u32 s5, s5, s6
	s_lshl_b64 s[6:7], s[4:5], 9
	v_and_b32_e32 v14, 63, v15
	s_add_u32 s6, s44, s6
	s_addc_u32 s7, s45, s7
	v_lshlrev_b32_e32 v42, 3, v14
	global_load_dwordx2 v[2:3], v42, s[6:7]
	v_and_b32_e32 v17, 15, v15
	v_bfe_u32 v4, v15, 4, 2
	v_bfe_u32 v6, v15, 2, 2
	v_and_b32_e32 v1, 7, v15
	v_lshlrev_b32_e32 v34, 3, v15
	v_mov_b32_e32 v7, 0x1000
	v_lshrrev_b32_e32 v9, 3, v15
	v_or_b32_e32 v12, 16, v17
	v_lshl_or_b32 v6, v4, 2, v6
	v_bfe_u32 v5, v15, 3, 1
	v_and_b32_e32 v10, 1, v15
	v_bitop3_b32 v13, v4, v1, 4 bitop3:0x36
	v_bitop3_b32 v16, v4, v15, 7 bitop3:0x78
	v_and_or_b32 v7, v34, 24, v7
	v_xor_b32_e32 v9, v9, v15
	v_mul_u32_u24_e32 v21, 0x40004, v14
	v_lshrrev_b32_e32 v22, 3, v12
	v_lshlrev_b32_e32 v24, 4, v6
	v_lshlrev_b32_e32 v6, 7, v6
	s_cmpk_gt_i32 s40, 0xff
	s_movk_i32 s6, 0x60
	v_lshlrev_b32_e32 v12, 7, v12
	v_xor_b32_e32 v23, v13, v5
	v_xor_b32_e32 v5, v16, v5
	v_and_or_b32 v9, v9, 6, v10
	v_or_b32_e32 v60, 0x10000, v21
	v_or_b32_e32 v61, 0x30002, v21
	v_xor_b32_e32 v10, v13, v22
	v_xor_b32_e32 v13, v16, v22
	v_or_b32_e32 v16, 0x800, v6
	v_or_b32_e32 v6, v6, v7
	s_cselect_b64 vcc, -1, 0
	v_lshlrev_b32_e32 v11, 6, v15
	s_waitcnt vmcnt(2)
	v_lshlrev_b32_e32 v52, 4, v9
	v_add_u32_e32 v9, s47, v42
	v_lshl_or_b32 v37, v10, 4, v12
	v_bitop3_b32 v10, v24, v16, s6 bitop3:0xce
	v_bitop3_b32 v39, v24, v6, s6 bitop3:0xce
	s_mul_hi_u32 s6, s4, 0x1200
	s_mulk_i32 s5, 0x1200
	s_mulk_i32 s4, 0x1200
	s_add_i32 s6, s6, s5
	v_mov_b32_e32 v43, 0
	s_add_u32 s4, s38, s4
	v_mov_b32_e32 v8, 0x60
	v_lshlrev_b32_e32 v19, 7, v17
	s_addc_u32 s5, s39, s6
	v_lshl_or_b32 v35, v23, 4, v19
	v_lshl_or_b32 v36, v5, 4, v19
	v_and_b32_e32 v5, 0x60, v24
	v_bitop3_b32 v19, v24, 64, v8 bitop3:0x6c
	v_bitop3_b32 v8, v24, 32, v8 bitop3:0x6c
	v_bfe_u32 v18, v15, 3, 3
	v_lshl_or_b32 v38, v13, 4, v12
	v_or_b32_e32 v12, v19, v16
	v_or_b32_e32 v13, v8, v16
	v_or_b32_e32 v41, v8, v6
	v_or_b32_e32 v8, v5, v16
	s_waitcnt vmcnt(1)
	v_or_b32_e32 v56, v6, v5
	v_lshlrev_b32_e32 v16, 3, v4
	v_and_b32_e32 v4, 48, v15
	v_mov_b32_e32 v5, v43
	v_lshlrev_b32_e32 v63, 6, v18
	v_bitop3_b32 v20, v18, v15, 7 bitop3:0x78
	v_or_b32_e32 v40, v19, v6
	v_add_u32_e32 v57, v10, v7
	v_add_u32_e32 v58, v12, v7
	v_add_u32_e32 v59, v13, v7
	v_add_u32_e32 v90, v8, v7
	v_add_u32_e32 v18, s47, v63
	v_mov_b32_e32 v19, v43
	v_lshlrev_b32_e32 v44, 4, v20
	v_mov_b32_e32 v45, v43
	s_mov_b32 m0, s46
	v_mov_b32_e32 v53, v43
	v_mov_b32_e32 v64, 9
	v_xor_b32_e32 v50, 16, v44
	v_mov_b32_e32 v51, v43
	v_xor_b32_e32 v48, 32, v44
	s_waitcnt vmcnt(0)
	v_cndmask_b32_e32 v2, v60, v2, vcc
	v_cndmask_b32_e32 v3, v61, v3, vcc
	ds_write_b64 v9, v[2:3]
	v_and_b32_e32 v2, 0xc0, v11
	v_lshlrev_b32_e32 v62, 1, v2
	v_lshl_or_b32 v2, s10, 9, v62
	v_mov_b32_e32 v3, v43
	v_lshl_add_u64 v[2:3], s[4:5], 0, v[2:3]
	s_lshl_b64 s[4:5], s[8:9], 22
	s_add_u32 s6, s80, s4
	v_lshl_add_u64 v[2:3], v[2:3], 0, v[4:5]
	s_addc_u32 s7, s81, s5
	global_load_dwordx4 v[10:13], v[2:3], off
	global_load_dwordx4 v[6:9], v[2:3], off offset:64
	s_waitcnt lgkmcnt(0)
	s_add_u32 s4, s37, s4
	ds_read_b128 v[30:33], v18
	ds_read_b128 v[22:25], v18 offset:16
	ds_read_b128 v[2:5], v18 offset:32
	ds_read_b128 v[26:29], v18 offset:48
	s_addc_u32 s5, s79, s5
	s_lshl_b32 s8, s10, 7
	s_add_u32 s4, s4, s8
	s_addc_u32 s5, s5, 0
	s_waitcnt lgkmcnt(3)
	v_lshlrev_b32_e32 v18, 9, v30
	s_add_u32 s6, s6, s8
	v_and_b32_e32 v18, 0x1fffe00, v18
	s_addc_u32 s7, s7, 0
	v_lshl_add_u64 v[20:21], s[4:5], 0, v[18:19]
	s_add_i32 s48, s46, 0x1000
	v_lshl_add_u64 v[20:21], v[20:21], 0, v[44:45]
	v_lshl_add_u64 v[18:19], s[6:7], 0, v[18:19]
	global_load_lds_dwordx4 v[20:21], off
	v_lshl_add_u64 v[18:19], v[18:19], 0, v[52:53]
	s_mov_b32 m0, s48
	s_add_i32 s49, s46, 0x400
	global_load_lds_dwordx4 v[18:19], off
	v_lshlrev_b32_sdwa v18, v64, v30 dst_sel:DWORD dst_unused:UNUSED_PAD src0_sel:DWORD src1_sel:WORD_1
	v_mov_b32_e32 v19, v43
	v_lshl_add_u64 v[20:21], s[4:5], 0, v[18:19]
	v_lshl_add_u64 v[20:21], v[20:21], 0, v[50:51]
	s_mov_b32 m0, s49
	v_lshl_add_u64 v[18:19], s[6:7], 0, v[18:19]
	s_add_i32 s50, s46, 0x1400
	global_load_lds_dwordx4 v[20:21], off
	v_lshl_add_u64 v[18:19], v[18:19], 0, v[52:53]
	s_mov_b32 m0, s50
	v_mov_b32_e32 v49, v43
	global_load_lds_dwordx4 v[18:19], off
	v_lshlrev_b32_e32 v18, 9, v31
	v_and_b32_e32 v18, 0x1fffe00, v18
	v_mov_b32_e32 v19, v43
	v_lshl_add_u64 v[20:21], s[4:5], 0, v[18:19]
	s_add_i32 s51, s46, 0x800
	v_lshl_add_u64 v[20:21], v[20:21], 0, v[48:49]
	s_mov_b32 m0, s51
	v_lshl_add_u64 v[18:19], s[6:7], 0, v[18:19]
	s_add_i32 s52, s46, 0x1800
	global_load_lds_dwordx4 v[20:21], off
	v_lshl_add_u64 v[18:19], v[18:19], 0, v[52:53]
	s_mov_b32 m0, s52
	v_xor_b32_e32 v46, 48, v44
	global_load_lds_dwordx4 v[18:19], off
	v_lshlrev_b32_sdwa v18, v64, v31 dst_sel:DWORD dst_unused:UNUSED_PAD src0_sel:DWORD src1_sel:WORD_1
	v_mov_b32_e32 v19, v43
	v_lshl_add_u64 v[20:21], s[4:5], 0, v[18:19]
	v_mov_b32_e32 v47, v43
	s_add_i32 s53, s46, 0xc00
	v_lshl_add_u64 v[20:21], v[20:21], 0, v[46:47]
	s_mov_b32 m0, s53
	v_lshl_add_u64 v[18:19], s[6:7], 0, v[18:19]
	s_add_i32 s54, s46, 0x1c00
	global_load_lds_dwordx4 v[20:21], off
	v_lshl_add_u64 v[18:19], v[18:19], 0, v[52:53]
	s_mov_b32 m0, s54
	v_cmp_gt_u32_e64 s[4:5], 4, v17
	global_load_lds_dwordx4 v[18:19], off
	v_and_b32_e32 v17, 0x80, v34
	v_bfe_u32 v15, v15, 5, 1
	v_or_b32_e32 v19, 32, v17
	v_or_b32_e32 v20, 64, v17
	v_or_b32_e32 v21, 0x60, v17
	v_or_b32_e32 v30, 6, v15
	v_or_b32_e32 v82, v17, v30
	v_or_b32_e32 v84, v19, v30
	v_or_b32_e32 v86, v20, v30
	v_or_b32_e32 v88, v21, v30
	v_or_b32_e32 v30, 10, v15
	v_or_b32_e32 v18, 2, v15
	v_or_b32_e32 v98, v17, v30
	v_or_b32_e32 v100, v19, v30
	v_or_b32_e32 v102, v20, v30
	v_or_b32_e32 v104, v21, v30
	v_or_b32_e32 v30, 14, v15
	v_or_b32_e32 v66, v17, v18
	v_or_b32_e32 v68, v19, v18
	v_or_b32_e32 v70, v20, v18
	v_or_b32_e32 v72, v21, v18
	v_or_b32_e32 v18, 4, v15
	v_or_b32_e32 v106, v17, v30
	v_or_b32_e32 v108, v19, v30
	v_or_b32_e32 v110, v20, v30
	v_or_b32_e32 v112, v21, v30
	v_or_b32_e32 v30, 18, v15
	v_or_b32_e32 v81, v17, v18
	v_or_b32_e32 v83, v19, v18
	v_or_b32_e32 v85, v20, v18
	v_or_b32_e32 v87, v21, v18
	v_or_b32_e32 v18, 8, v15
	v_or_b32_e32 v114, v17, v30
	v_or_b32_e32 v116, v19, v30
	v_or_b32_e32 v118, v20, v30
	v_or_b32_e32 v120, v21, v30
	v_or_b32_e32 v30, 22, v15
	v_lshl_add_u64 v[54:55], s[44:45], 0, v[42:43]
	v_or_b32_e32 v97, v17, v18
	v_or_b32_e32 v99, v19, v18
	v_or_b32_e32 v101, v20, v18
	v_or_b32_e32 v103, v21, v18
	v_or_b32_e32 v18, 12, v15
	v_or_b32_e32 v122, v17, v30
	v_or_b32_e32 v124, v19, v30
	v_or_b32_e32 v126, v20, v30
	v_or_b32_e32 v128, v21, v30
	v_or_b32_e32 v30, 26, v15
	s_abs_i32 s45, s42
	v_or_b32_e32 v105, v17, v18
	v_or_b32_e32 v107, v19, v18
	v_or_b32_e32 v109, v20, v18
	v_or_b32_e32 v111, v21, v18
	v_or_b32_e32 v18, 16, v15
	v_or_b32_e32 v130, v17, v30
	v_or_b32_e32 v132, v19, v30
	v_or_b32_e32 v134, v20, v30
	v_or_b32_e32 v136, v21, v30
	v_cvt_f32_u32_e32 v30, s45
	v_or_b32_e32 v113, v17, v18
	v_or_b32_e32 v115, v19, v18
	v_or_b32_e32 v117, v20, v18
	v_or_b32_e32 v119, v21, v18
	v_or_b32_e32 v18, 20, v15
	v_or_b32_e32 v121, v17, v18
	v_or_b32_e32 v123, v19, v18
	v_or_b32_e32 v125, v20, v18
	v_or_b32_e32 v127, v21, v18
	v_or_b32_e32 v18, 24, v15
	v_or_b32_e32 v65, v17, v15
	v_or_b32_e32 v67, v19, v15
	v_or_b32_e32 v69, v20, v15
	v_or_b32_e32 v71, v21, v15
	v_or_b32_e32 v129, v17, v18
	v_or_b32_e32 v131, v19, v18
	v_or_b32_e32 v133, v20, v18
	v_or_b32_e32 v135, v21, v18
	v_or_b32_e32 v18, 28, v15
	v_or_b32_e32 v15, 30, v15
	v_or_b32_e32 v137, v17, v18
	v_or_b32_e32 v138, v17, v15
	v_rcp_iflag_f32_e32 v17, v30
	s_sub_i32 s8, 0, s45
	s_add_i32 s44, s46, 0x2000
	v_lshlrev_b32_e32 v1, 2, v14
	v_mul_f32_e32 v17, 0x4f7ffffe, v17
	v_cvt_u32_f32_e32 v17, v17
	s_waitcnt vmcnt(0)
	v_cndmask_b32_e64 v9, 0, v9, s[4:5]
	v_cndmask_b32_e64 v8, 0, v8, s[4:5]
	v_cndmask_b32_e64 v7, 0, v7, s[4:5]
	v_readfirstlane_b32 s10, v17
	s_mul_i32 s8, s8, s10
	s_mul_hi_u32 s8, s10, s8
	v_cndmask_b32_e64 v6, 0, v6, s[4:5]
	v_cndmask_b32_e64 v13, 0, v13, s[4:5]
	v_cndmask_b32_e64 v12, 0, v12, s[4:5]
	v_cndmask_b32_e64 v11, 0, v11, s[4:5]
	v_cndmask_b32_e64 v10, 0, v10, s[4:5]
	v_cmp_gt_u32_e64 s[6:7], 16, v14
	v_add_u32_e32 v73, s46, v56
	v_add_u32_e32 v74, s46, v90
	v_add_u32_e32 v75, s46, v41
	v_add_u32_e32 v76, s46, v59
	v_add_u32_e32 v77, s46, v40
	v_add_u32_e32 v78, s46, v58
	v_add_u32_e32 v79, s46, v39
	v_add_u32_e32 v80, s46, v57
	v_add_u32_e32 v89, s44, v56
	v_add_u32_e32 v90, s44, v90
	v_add_u32_e32 v91, s44, v41
	v_add_u32_e32 v92, s44, v59
	v_add_u32_e32 v93, s44, v40
	v_add_u32_e32 v94, s44, v58
	v_add_u32_e32 v95, s44, v39
	v_add_u32_e32 v96, s44, v57
	v_or_b32_e32 v139, v19, v18
	v_or_b32_e32 v140, v19, v15
	v_or_b32_e32 v141, v20, v18
	v_or_b32_e32 v142, v20, v15
	v_or_b32_e32 v143, v21, v18
	v_or_b32_e32 v144, v21, v15
	s_ashr_i32 s55, s42, 31
	s_add_i32 s56, s10, s8
	s_sub_i32 s57, 0, s42
	v_lshlrev_b32_e32 v56, 1, v16
	s_add_i32 s58, s46, 0x3000
	s_add_i32 s59, s46, 0x2400
	s_add_i32 s60, s46, 0x3400
	s_add_i32 s61, s46, 0x2800
	s_add_i32 s64, s46, 0x3800
	s_add_i32 s65, s46, 0x2c00
	s_add_i32 s66, s46, 0x3c00
	v_add_u32_e32 v145, s46, v36
	v_add_u32_e32 v149, s46, v35
	v_add_u32_e32 v151, s46, v38
	v_add_u32_e32 v153, s46, v37
	v_lshlrev_b32_e32 v58, 1, v14
	s_movk_i32 s67, 0x7fff
	s_mov_b32 s69, 0
	s_mov_b32 s70, 0
	s_branch .LBB0_978
